# K-loop: opening barrier of each MFMA block moved 4 MFMAs down and the DMA vmcnt wait moved down to it; coalesced epilogue stores
# baseline (speedup 1.0000x reference)
; #define PG8_STAGE(bufoff, gbase, voff) do { _Pragma("unroll") for (int _i = 0; _i < 2; ++_i) \
;         __builtin_amdgcn_global_load_lds((const unsigned*)((const char*)(gbase) + (voff)[_i]), (PG8_LAS unsigned*)(lds + (bufoff) + ldsw + _i * 8192), 16, 0, 0); } while (0)
; #define PG8_LDA(dst, b, h) do { _Pragma("unroll") for (int m = 0; m < 4; ++m) _Pragma("unroll") for (int k = 0; k < 2; ++k) dst[m][k] = *(const PG8_LAS bf16x8*)(lds + PG8_SA(b, h) + aoff + m * 2048 + k * 1024); } while (0)
; #define PG8_LDB(dst, b, h) do { _Pragma("unroll") for (int n = 0; n < 2; ++n) _Pragma("unroll") for (int k = 0; k < 2; ++k) dst[n][k] = *(const PG8_LAS bf16x8*)(lds + PG8_SB(b, h) + boff + n * 2048 + k * 1024); } while (0)
; #define PG8_MMA(ai, bj, At, Bt) do { __builtin_amdgcn_s_setprio(1); _Pragma("unroll") for (int m = 0; m < 4; ++m) _Pragma("unroll") for (int n = 0; n < 2; ++n) _Pragma("unroll") for (int k = 0; k < 2; ++k) \
;         acc[ai][bj][m][n] = __builtin_amdgcn_mfma_f32_16x16x32_bf16(Bt[n][k], At[m][k], acc[ai][bj][m][n], 0, 0, 0); __builtin_amdgcn_s_setprio(0); } while (0)
; #define PG8_WAIT_V(n) asm volatile("s_waitcnt vmcnt(" #n ")" ::: "memory")
; #define PG8_WAIT_L(n) asm volatile("s_waitcnt lgkmcnt(" #n ")" ::: "memory")
; #define PG8_BAR __builtin_amdgcn_s_barrier()
; #define PG8_SCHED __builtin_amdgcn_sched_barrier(0)
; template <class Epi, class Sched, bool ALIGN_EPI = false, bool SP2 = false>
; __device__ __forceinline__ void gemm_phase(PG8_LAS unsigned char* lds, const Gemm g, const Sched& S, const Epi& E, const int wid_in) {
;     ...
;             PG8_LDB(B0, 0, 0); PG8_LDB(B1, 0, 1); PG8_SCHED; PG8_LDA(At, 0, 0); PG8_STAGE(PG8_SA(1, 1), a1 + hstepA, voffA);
;             PG8_WAIT_V(8); PG8_WAIT_L(0); PG8_BAR; PG8_MMA(0, 0, At, B0); PG8_MMA(0, 1, At, B1); PG8_BAR; PG8_SCHED;
;             PG8_LDA(At, 0, 1); PG8_STAGE(PG8_SB(0, 0), b2, voffB); PG8_STAGE(PG8_SB(0, 1), b2 + hstep, voffB); PG8_STAGE(PG8_SA(0, 0), a2, voffA);
;             PG8_WAIT_V(8); PG8_WAIT_L(0); PG8_BAR; PG8_MMA(1, 0, At, B0); PG8_MMA(1, 1, At, B1); PG8_BAR; PG8_SCHED;
.LBB0_119:
	s_add_u32 s2, s4, 0xfff80080
	s_addc_u32 s3, s5, -1
	s_add_i32 s47, 0, 0x10000
	s_cmp_eq_u32 s46, 28
	s_cselect_b32 s23, s17, s3
	s_cselect_b32 s22, s42, s2
	s_cselect_b32 s3, s15, s45
	s_cselect_b32 s2, s43, s44
	s_add_i32 s50, 0, 0x14000
	v_add_u32_e32 v142, s47, v202
	s_waitcnt lgkmcnt(0)
	v_add_u32_e32 v184, s50, v202
	ds_read_b128 v[130:133], v142
	ds_read_b128 v[134:137], v142 offset:1024
	ds_read_b128 v[138:141], v142 offset:2048
	ds_read_b128 v[142:145], v142 offset:3072
	ds_read_b128 v[146:149], v184
	ds_read_b128 v[150:153], v184 offset:1024
	ds_read_b128 v[180:183], v184 offset:2048
	ds_read_b128 v[184:187], v184 offset:3072
	v_lshl_add_u64 v[234:235], s[4:5], 0, v[176:177]
	s_add_i32 m0, s34, 0xc000
	ds_read_b128 v[188:191], v205
	ds_read_b128 v[206:209], v205 offset:1024
	ds_read_b128 v[210:213], v205 offset:2048
	ds_read_b128 v[214:217], v205 offset:3072
	ds_read_b128 v[218:221], v205 offset:4096
	ds_read_b128 v[222:225], v205 offset:5120
	ds_read_b128 v[226:229], v205 offset:6144
	ds_read_b128 v[230:233], v205 offset:7168
	global_load_lds_dwordx4 v[234:235], off
	v_lshl_add_u64 v[234:235], s[4:5], 0, v[178:179]
	s_add_i32 m0, s34, 0xe000
	s_nop 0
	global_load_lds_dwordx4 v[234:235], off
	s_waitcnt lgkmcnt(0)
	s_setprio 1
	s_waitcnt lgkmcnt(0)
	v_mfma_f32_16x16x32_bf16 v[126:129], v[130:133], v[188:191], v[126:129]
	v_mfma_f32_16x16x32_bf16 v[122:125], v[138:141], v[188:191], v[122:125]
	v_mfma_f32_16x16x32_bf16 v[110:113], v[130:133], v[210:213], v[110:113]
	v_mfma_f32_16x16x32_bf16 v[106:109], v[138:141], v[210:213], v[106:109]
	s_waitcnt vmcnt(8)
	s_barrier
	v_mfma_f32_16x16x32_bf16 v[94:97], v[130:133], v[218:221], v[94:97]
	v_mfma_f32_16x16x32_bf16 v[90:93], v[138:141], v[218:221], v[90:93]
	v_mfma_f32_16x16x32_bf16 v[78:81], v[130:133], v[226:229], v[78:81]
	v_mfma_f32_16x16x32_bf16 v[74:77], v[138:141], v[226:229], v[74:77]
	v_mfma_f32_16x16x32_bf16 v[126:129], v[134:137], v[206:209], v[126:129]
	v_mfma_f32_16x16x32_bf16 v[122:125], v[142:145], v[206:209], v[122:125]
	v_mfma_f32_16x16x32_bf16 v[110:113], v[134:137], v[214:217], v[110:113]
	v_mfma_f32_16x16x32_bf16 v[106:109], v[142:145], v[214:217], v[106:109]
	v_mfma_f32_16x16x32_bf16 v[94:97], v[134:137], v[222:225], v[94:97]
	v_mfma_f32_16x16x32_bf16 v[90:93], v[142:145], v[222:225], v[90:93]
	v_mfma_f32_16x16x32_bf16 v[78:81], v[134:137], v[230:233], v[78:81]
	v_mfma_f32_16x16x32_bf16 v[74:77], v[142:145], v[230:233], v[74:77]
	s_setprio 0
	s_setprio 1
	v_mfma_f32_16x16x32_bf16 v[118:121], v[146:149], v[188:191], v[118:121]
	v_mfma_f32_16x16x32_bf16 v[114:117], v[180:183], v[188:191], v[114:117]
	v_mfma_f32_16x16x32_bf16 v[102:105], v[146:149], v[210:213], v[102:105]
	v_mfma_f32_16x16x32_bf16 v[98:101], v[180:183], v[210:213], v[98:101]
	v_mfma_f32_16x16x32_bf16 v[86:89], v[146:149], v[218:221], v[86:89]
	v_mfma_f32_16x16x32_bf16 v[82:85], v[180:183], v[218:221], v[82:85]
	v_mfma_f32_16x16x32_bf16 v[70:73], v[146:149], v[226:229], v[70:73]
	v_mfma_f32_16x16x32_bf16 v[66:69], v[180:183], v[226:229], v[66:69]
	v_mfma_f32_16x16x32_bf16 v[118:121], v[150:153], v[206:209], v[118:121]
	v_mfma_f32_16x16x32_bf16 v[114:117], v[184:187], v[206:209], v[114:117]
	v_mfma_f32_16x16x32_bf16 v[102:105], v[150:153], v[214:217], v[102:105]
	v_mfma_f32_16x16x32_bf16 v[98:101], v[184:187], v[214:217], v[98:101]
	v_mfma_f32_16x16x32_bf16 v[86:89], v[150:153], v[222:225], v[86:89]
	v_mfma_f32_16x16x32_bf16 v[82:85], v[184:187], v[222:225], v[82:85]
	v_mfma_f32_16x16x32_bf16 v[70:73], v[150:153], v[230:233], v[70:73]
	v_mfma_f32_16x16x32_bf16 v[66:69], v[184:187], v[230:233], v[66:69]
	s_setprio 0
	s_barrier
	s_add_i32 s47, s47, s27
	v_lshl_add_u64 v[234:235], s[2:3], 0, v[170:171]
	s_mov_b32 m0, s47
	ds_read_b128 v[188:191], v205 offset:16384
	ds_read_b128 v[206:209], v205 offset:17408
	ds_read_b128 v[210:213], v205 offset:18432
	ds_read_b128 v[214:217], v205 offset:19456
	ds_read_b128 v[218:221], v205 offset:20480
	ds_read_b128 v[222:225], v205 offset:21504
	ds_read_b128 v[226:229], v205 offset:22528
	ds_read_b128 v[230:233], v205 offset:23552
	global_load_lds_dwordx4 v[234:235], off
	s_add_i32 m0, s47, 0x2000
	s_add_u32 s48, s2, 0x80000
	v_lshl_add_u64 v[236:237], s[2:3], 0, v[166:167]
	s_addc_u32 s49, s3, 0
	s_add_i32 s47, s50, s27
	global_load_lds_dwordx4 v[236:237], off
	v_lshl_add_u64 v[238:239], s[48:49], 0, v[170:171]
	s_mov_b32 m0, s47
	v_lshl_add_u64 v[240:241], s[22:23], 0, v[168:169]
	global_load_lds_dwordx4 v[238:239], off
	v_lshl_add_u64 v[238:239], s[48:49], 0, v[166:167]
	s_add_i32 m0, s47, 0x2000
	s_nop 0
	global_load_lds_dwordx4 v[238:239], off
	v_lshl_add_u64 v[238:239], s[22:23], 0, v[172:173]
	s_mov_b32 m0, s34
	s_nop 0
	global_load_lds_dwordx4 v[238:239], off
	s_mov_b32 m0, s35
	s_nop 0
	global_load_lds_dwordx4 v[240:241], off
	s_waitcnt lgkmcnt(0)
	s_setprio 1
	s_waitcnt lgkmcnt(0)
	v_mfma_f32_16x16x32_bf16 v[62:65], v[130:133], v[188:191], v[62:65]
	v_mfma_f32_16x16x32_bf16 v[58:61], v[138:141], v[188:191], v[58:61]
	v_mfma_f32_16x16x32_bf16 v[46:49], v[130:133], v[210:213], v[46:49]
	v_mfma_f32_16x16x32_bf16 v[42:45], v[138:141], v[210:213], v[42:45]
	s_waitcnt vmcnt(8)
	s_barrier
; #define PG8_STAGE(bufoff, gbase, voff) do { _Pragma("unroll") for (int _i = 0; _i < 2; ++_i) \
;         __builtin_amdgcn_global_load_lds((const unsigned*)((const char*)(gbase) + (voff)[_i]), (PG8_LAS unsigned*)(lds + (bufoff) + ldsw + _i * 8192), 16, 0, 0); } while (0)
; #define PG8_LDA(dst, b, h) do { _Pragma("unroll") for (int m = 0; m < 4; ++m) _Pragma("unroll") for (int k = 0; k < 2; ++k) dst[m][k] = *(const PG8_LAS bf16x8*)(lds + PG8_SA(b, h) + aoff + m * 2048 + k * 1024); } while (0)
; #define PG8_LDB(dst, b, h) do { _Pragma("unroll") for (int n = 0; n < 2; ++n) _Pragma("unroll") for (int k = 0; k < 2; ++k) dst[n][k] = *(const PG8_LAS bf16x8*)(lds + PG8_SB(b, h) + boff + n * 2048 + k * 1024); } while (0)
; #define PG8_MMA(ai, bj, At, Bt) do { __builtin_amdgcn_s_setprio(1); _Pragma("unroll") for (int m = 0; m < 4; ++m) _Pragma("unroll") for (int n = 0; n < 2; ++n) _Pragma("unroll") for (int k = 0; k < 2; ++k) \
;         acc[ai][bj][m][n] = __builtin_amdgcn_mfma_f32_16x16x32_bf16(Bt[n][k], At[m][k], acc[ai][bj][m][n], 0, 0, 0); __builtin_amdgcn_s_setprio(0); } while (0)
; #define PG8_WAIT_V(n) asm volatile("s_waitcnt vmcnt(" #n ")" ::: "memory")
; #define PG8_WAIT_L(n) asm volatile("s_waitcnt lgkmcnt(" #n ")" ::: "memory")
; #define PG8_BAR __builtin_amdgcn_s_barrier()
; #define PG8_SCHED __builtin_amdgcn_sched_barrier(0)
; template <class Epi, class Sched, bool ALIGN_EPI = false, bool SP2 = false>
; __device__ __forceinline__ void gemm_phase(PG8_LAS unsigned char* lds, const Gemm g, const Sched& S, const Epi& E, const int wid_in) {
;     ...
;             PG8_WAIT_V(8); PG8_WAIT_L(0); PG8_BAR; PG8_MMA(1, 0, At, B0); PG8_MMA(1, 1, At, B1); PG8_BAR; PG8_SCHED;
;             PG8_LDB(B0, 1, 0); PG8_LDB(B1, 1, 1); PG8_SCHED; PG8_LDA(At, 1, 0); PG8_STAGE(PG8_SA(0, 1), a2 + hstepA, voffA);
;             PG8_WAIT_V(8); PG8_WAIT_L(0); PG8_BAR; PG8_MMA(0, 0, At, B0); PG8_MMA(0, 1, At, B1); PG8_BAR; PG8_SCHED;
;             PG8_LDA(At, 1, 1); PG8_STAGE(PG8_SB(1, 0), b3, voffB); PG8_STAGE(PG8_SB(1, 1), b3 + hstep, voffB); PG8_STAGE(PG8_SA(1, 0), a3, voffA);
	v_mfma_f32_16x16x32_bf16 v[30:33], v[130:133], v[218:221], v[30:33]
	v_mfma_f32_16x16x32_bf16 v[26:29], v[138:141], v[218:221], v[26:29]
	v_mfma_f32_16x16x32_bf16 v[14:17], v[130:133], v[226:229], v[14:17]
	v_mfma_f32_16x16x32_bf16 v[10:13], v[138:141], v[226:229], v[10:13]
	v_mfma_f32_16x16x32_bf16 v[62:65], v[134:137], v[206:209], v[62:65]
	v_mfma_f32_16x16x32_bf16 v[58:61], v[142:145], v[206:209], v[58:61]
	v_mfma_f32_16x16x32_bf16 v[46:49], v[134:137], v[214:217], v[46:49]
	v_mfma_f32_16x16x32_bf16 v[42:45], v[142:145], v[214:217], v[42:45]
	v_mfma_f32_16x16x32_bf16 v[30:33], v[134:137], v[222:225], v[30:33]
	v_mfma_f32_16x16x32_bf16 v[26:29], v[142:145], v[222:225], v[26:29]
	v_mfma_f32_16x16x32_bf16 v[14:17], v[134:137], v[230:233], v[14:17]
	v_mfma_f32_16x16x32_bf16 v[10:13], v[142:145], v[230:233], v[10:13]
	s_setprio 0
	s_setprio 1
	v_mfma_f32_16x16x32_bf16 v[54:57], v[146:149], v[188:191], v[54:57]
	v_mfma_f32_16x16x32_bf16 v[50:53], v[180:183], v[188:191], v[50:53]
	v_mfma_f32_16x16x32_bf16 v[38:41], v[146:149], v[210:213], v[38:41]
	v_mfma_f32_16x16x32_bf16 v[34:37], v[180:183], v[210:213], v[34:37]
	v_mfma_f32_16x16x32_bf16 v[22:25], v[146:149], v[218:221], v[22:25]
	v_mfma_f32_16x16x32_bf16 v[18:21], v[180:183], v[218:221], v[18:21]
	v_mfma_f32_16x16x32_bf16 v[6:9], v[146:149], v[226:229], v[6:9]
	v_mfma_f32_16x16x32_bf16 v[2:5], v[180:183], v[226:229], v[2:5]
	v_mfma_f32_16x16x32_bf16 v[54:57], v[150:153], v[206:209], v[54:57]
	v_mfma_f32_16x16x32_bf16 v[50:53], v[184:187], v[206:209], v[50:53]
	v_mfma_f32_16x16x32_bf16 v[38:41], v[150:153], v[214:217], v[38:41]
	v_mfma_f32_16x16x32_bf16 v[34:37], v[184:187], v[214:217], v[34:37]
	v_mfma_f32_16x16x32_bf16 v[22:25], v[150:153], v[222:225], v[22:25]
	v_mfma_f32_16x16x32_bf16 v[18:21], v[184:187], v[222:225], v[18:21]
	v_mfma_f32_16x16x32_bf16 v[6:9], v[150:153], v[230:233], v[6:9]
	v_mfma_f32_16x16x32_bf16 v[2:5], v[184:187], v[230:233], v[2:5]
	s_setprio 0
	s_barrier
	s_add_i32 s47, 0, 0x18000
	s_add_i32 s48, 0, 0x1c000
	v_add_u32_e32 v142, s47, v202
	v_add_u32_e32 v184, s48, v202
	ds_read_b128 v[130:133], v142
	ds_read_b128 v[134:137], v142 offset:1024
	ds_read_b128 v[138:141], v142 offset:2048
	ds_read_b128 v[142:145], v142 offset:3072
	ds_read_b128 v[146:149], v184
	ds_read_b128 v[150:153], v184 offset:1024
	ds_read_b128 v[180:183], v184 offset:2048
	ds_read_b128 v[184:187], v184 offset:3072
	s_add_u32 s22, s22, 0x80000
	s_addc_u32 s23, s23, 0
	s_mov_b32 m0, s36
	v_lshl_add_u64 v[242:243], s[22:23], 0, v[172:173]
	ds_read_b128 v[188:191], v205 offset:32768
	ds_read_b128 v[206:209], v205 offset:33792
	ds_read_b128 v[210:213], v205 offset:34816
	ds_read_b128 v[214:217], v205 offset:35840
	ds_read_b128 v[218:221], v205 offset:36864
	ds_read_b128 v[222:225], v205 offset:37888
	ds_read_b128 v[226:229], v205 offset:38912
	ds_read_b128 v[230:233], v205 offset:39936
	global_load_lds_dwordx4 v[242:243], off
	v_lshl_add_u64 v[242:243], s[22:23], 0, v[168:169]
	s_mov_b32 m0, s37
	s_nop 0
	global_load_lds_dwordx4 v[242:243], off
	s_waitcnt lgkmcnt(0)
	s_setprio 1
	s_waitcnt lgkmcnt(0)
	v_mfma_f32_16x16x32_bf16 v[126:129], v[130:133], v[188:191], v[126:129]
	v_mfma_f32_16x16x32_bf16 v[122:125], v[138:141], v[188:191], v[122:125]
	v_mfma_f32_16x16x32_bf16 v[110:113], v[130:133], v[210:213], v[110:113]
	v_mfma_f32_16x16x32_bf16 v[106:109], v[138:141], v[210:213], v[106:109]
	s_waitcnt vmcnt(8)
	s_barrier
	v_mfma_f32_16x16x32_bf16 v[94:97], v[130:133], v[218:221], v[94:97]
	v_mfma_f32_16x16x32_bf16 v[90:93], v[138:141], v[218:221], v[90:93]
	v_mfma_f32_16x16x32_bf16 v[78:81], v[130:133], v[226:229], v[78:81]
	v_mfma_f32_16x16x32_bf16 v[74:77], v[138:141], v[226:229], v[74:77]
	v_mfma_f32_16x16x32_bf16 v[126:129], v[134:137], v[206:209], v[126:129]
	v_mfma_f32_16x16x32_bf16 v[122:125], v[142:145], v[206:209], v[122:125]
	v_mfma_f32_16x16x32_bf16 v[110:113], v[134:137], v[214:217], v[110:113]
	v_mfma_f32_16x16x32_bf16 v[106:109], v[142:145], v[214:217], v[106:109]
	v_mfma_f32_16x16x32_bf16 v[94:97], v[134:137], v[222:225], v[94:97]
	v_mfma_f32_16x16x32_bf16 v[90:93], v[142:145], v[222:225], v[90:93]
	v_mfma_f32_16x16x32_bf16 v[78:81], v[134:137], v[230:233], v[78:81]
	v_mfma_f32_16x16x32_bf16 v[74:77], v[142:145], v[230:233], v[74:77]
	s_setprio 0
	s_setprio 1
	v_mfma_f32_16x16x32_bf16 v[118:121], v[146:149], v[188:191], v[118:121]
	v_mfma_f32_16x16x32_bf16 v[114:117], v[180:183], v[188:191], v[114:117]
	v_mfma_f32_16x16x32_bf16 v[102:105], v[146:149], v[210:213], v[102:105]
	v_mfma_f32_16x16x32_bf16 v[98:101], v[180:183], v[210:213], v[98:101]
	v_mfma_f32_16x16x32_bf16 v[86:89], v[146:149], v[218:221], v[86:89]
	v_mfma_f32_16x16x32_bf16 v[82:85], v[180:183], v[218:221], v[82:85]
	v_mfma_f32_16x16x32_bf16 v[70:73], v[146:149], v[226:229], v[70:73]
	v_mfma_f32_16x16x32_bf16 v[66:69], v[180:183], v[226:229], v[66:69]
	v_mfma_f32_16x16x32_bf16 v[118:121], v[150:153], v[206:209], v[118:121]
	v_mfma_f32_16x16x32_bf16 v[114:117], v[184:187], v[206:209], v[114:117]
	v_mfma_f32_16x16x32_bf16 v[102:105], v[150:153], v[214:217], v[102:105]
	v_mfma_f32_16x16x32_bf16 v[98:101], v[184:187], v[214:217], v[98:101]
	v_mfma_f32_16x16x32_bf16 v[86:89], v[150:153], v[222:225], v[86:89]
	v_mfma_f32_16x16x32_bf16 v[82:85], v[184:187], v[222:225], v[82:85]
	v_mfma_f32_16x16x32_bf16 v[70:73], v[150:153], v[230:233], v[70:73]
	v_mfma_f32_16x16x32_bf16 v[66:69], v[184:187], v[230:233], v[66:69]
	s_setprio 0
	s_barrier
; #define PG8_STAGE(bufoff, gbase, voff) do { _Pragma("unroll") for (int _i = 0; _i < 2; ++_i) \
;         __builtin_amdgcn_global_load_lds((const unsigned*)((const char*)(gbase) + (voff)[_i]), (PG8_LAS unsigned*)(lds + (bufoff) + ldsw + _i * 8192), 16, 0, 0); } while (0)
; #define PG8_LDA(dst, b, h) do { _Pragma("unroll") for (int m = 0; m < 4; ++m) _Pragma("unroll") for (int k = 0; k < 2; ++k) dst[m][k] = *(const PG8_LAS bf16x8*)(lds + PG8_SA(b, h) + aoff + m * 2048 + k * 1024); } while (0)
; #define PG8_MMA(ai, bj, At, Bt) do { __builtin_amdgcn_s_setprio(1); _Pragma("unroll") for (int m = 0; m < 4; ++m) _Pragma("unroll") for (int n = 0; n < 2; ++n) _Pragma("unroll") for (int k = 0; k < 2; ++k) \
;         acc[ai][bj][m][n] = __builtin_amdgcn_mfma_f32_16x16x32_bf16(Bt[n][k], At[m][k], acc[ai][bj][m][n], 0, 0, 0); __builtin_amdgcn_s_setprio(0); } while (0)
; #define PG8_WAIT_V(n) asm volatile("s_waitcnt vmcnt(" #n ")" ::: "memory")
; #define PG8_WAIT_L(n) asm volatile("s_waitcnt lgkmcnt(" #n ")" ::: "memory")
; #define PG8_BAR __builtin_amdgcn_s_barrier()
; #define PG8_SCHED __builtin_amdgcn_sched_barrier(0)
; template <class Epi, class Sched, bool ALIGN_EPI = false, bool SP2 = false>
; __device__ __forceinline__ void gemm_phase(PG8_LAS unsigned char* lds, const Gemm g, const Sched& S, const Epi& E, const int wid_in) {
;     ...
;             PG8_LDA(At, 1, 1); PG8_STAGE(PG8_SB(1, 0), b3, voffB); PG8_STAGE(PG8_SB(1, 1), b3 + hstep, voffB); PG8_STAGE(PG8_SA(1, 0), a3, voffA);
;             PG8_WAIT_V(8); PG8_WAIT_L(0); PG8_BAR; PG8_MMA(1, 0, At, B0); PG8_MMA(1, 1, At, B1); PG8_BAR; PG8_SCHED;
	s_add_i32 s22, s47, s27
	v_lshl_add_u64 v[234:235], v[234:235], 0, s[98:99]
	s_mov_b32 m0, s22
	ds_read_b128 v[188:191], v205 offset:49152
	ds_read_b128 v[206:209], v205 offset:50176
	ds_read_b128 v[210:213], v205 offset:51200
	ds_read_b128 v[214:217], v205 offset:52224
	ds_read_b128 v[218:221], v205 offset:53248
	ds_read_b128 v[222:225], v205 offset:54272
	ds_read_b128 v[226:229], v205 offset:55296
	ds_read_b128 v[230:233], v205 offset:56320
	global_load_lds_dwordx4 v[234:235], off
	s_add_i32 m0, s22, 0x2000
	s_add_u32 s2, s2, 0x80080
	v_lshl_add_u64 v[234:235], v[236:237], 0, s[98:99]
	s_addc_u32 s3, s3, 0
	s_add_i32 s22, s48, s27
	global_load_lds_dwordx4 v[234:235], off
	v_lshl_add_u64 v[234:235], s[2:3], 0, v[170:171]
	s_mov_b32 m0, s22
	s_nop 0
	global_load_lds_dwordx4 v[234:235], off
	v_lshl_add_u64 v[234:235], s[2:3], 0, v[166:167]
	s_add_i32 m0, s22, 0x2000
	s_nop 0
	global_load_lds_dwordx4 v[234:235], off
	v_lshl_add_u64 v[234:235], v[238:239], 0, s[98:99]
	s_mov_b32 m0, s38
	s_nop 0
	global_load_lds_dwordx4 v[234:235], off
	v_lshl_add_u64 v[234:235], v[240:241], 0, s[98:99]
	s_mov_b32 m0, s39
	s_nop 0
	global_load_lds_dwordx4 v[234:235], off
	s_waitcnt lgkmcnt(0)
	s_setprio 1
	s_waitcnt lgkmcnt(0)
	v_mfma_f32_16x16x32_bf16 v[62:65], v[130:133], v[188:191], v[62:65]
	v_mfma_f32_16x16x32_bf16 v[58:61], v[138:141], v[188:191], v[58:61]
	v_mfma_f32_16x16x32_bf16 v[46:49], v[130:133], v[210:213], v[46:49]
	v_mfma_f32_16x16x32_bf16 v[42:45], v[138:141], v[210:213], v[42:45]
	s_waitcnt vmcnt(8)
	s_barrier
	v_mfma_f32_16x16x32_bf16 v[30:33], v[130:133], v[218:221], v[30:33]
	v_mfma_f32_16x16x32_bf16 v[26:29], v[138:141], v[218:221], v[26:29]
	v_mfma_f32_16x16x32_bf16 v[14:17], v[130:133], v[226:229], v[14:17]
	v_mfma_f32_16x16x32_bf16 v[10:13], v[138:141], v[226:229], v[10:13]
	v_mfma_f32_16x16x32_bf16 v[62:65], v[134:137], v[206:209], v[62:65]
	v_mfma_f32_16x16x32_bf16 v[58:61], v[142:145], v[206:209], v[58:61]
	v_mfma_f32_16x16x32_bf16 v[46:49], v[134:137], v[214:217], v[46:49]
	v_mfma_f32_16x16x32_bf16 v[42:45], v[142:145], v[214:217], v[42:45]
	v_mfma_f32_16x16x32_bf16 v[30:33], v[134:137], v[222:225], v[30:33]
	v_mfma_f32_16x16x32_bf16 v[26:29], v[142:145], v[222:225], v[26:29]
	v_mfma_f32_16x16x32_bf16 v[14:17], v[134:137], v[230:233], v[14:17]
	v_mfma_f32_16x16x32_bf16 v[10:13], v[142:145], v[230:233], v[10:13]
	s_setprio 0
	s_setprio 1
	v_mfma_f32_16x16x32_bf16 v[54:57], v[146:149], v[188:191], v[54:57]
	v_mfma_f32_16x16x32_bf16 v[50:53], v[180:183], v[188:191], v[50:53]
	v_mfma_f32_16x16x32_bf16 v[38:41], v[146:149], v[210:213], v[38:41]
	v_mfma_f32_16x16x32_bf16 v[34:37], v[180:183], v[210:213], v[34:37]
	v_mfma_f32_16x16x32_bf16 v[22:25], v[146:149], v[218:221], v[22:25]
	v_mfma_f32_16x16x32_bf16 v[18:21], v[180:183], v[218:221], v[18:21]
	v_mfma_f32_16x16x32_bf16 v[6:9], v[146:149], v[226:229], v[6:9]
	v_mfma_f32_16x16x32_bf16 v[2:5], v[180:183], v[226:229], v[2:5]
	v_mfma_f32_16x16x32_bf16 v[54:57], v[150:153], v[206:209], v[54:57]
	v_mfma_f32_16x16x32_bf16 v[50:53], v[184:187], v[206:209], v[50:53]
	v_mfma_f32_16x16x32_bf16 v[38:41], v[150:153], v[214:217], v[38:41]
	v_mfma_f32_16x16x32_bf16 v[34:37], v[184:187], v[214:217], v[34:37]
	v_mfma_f32_16x16x32_bf16 v[22:25], v[150:153], v[222:225], v[22:25]
	v_mfma_f32_16x16x32_bf16 v[18:21], v[184:187], v[222:225], v[18:21]
	v_mfma_f32_16x16x32_bf16 v[6:9], v[150:153], v[230:233], v[6:9]
	v_mfma_f32_16x16x32_bf16 v[2:5], v[184:187], v[230:233], v[2:5]
	s_setprio 0
	s_barrier
	s_add_i32 s46, s46, 2
	s_add_u32 s4, s4, 0x100
	s_addc_u32 s5, s5, 0
	s_add_u32 s44, s44, 0x100
	s_addc_u32 s45, s45, 0
	s_cmp_gt_u32 s46, 29
	s_cbranch_scc0 .LBB0_119
	s_and_b64 vcc, exec, s[12:13]
	s_cbranch_vccz .LBB0_122
	s_barrier

; #define PG8_STAGE(bufoff, gbase, voff) do { _Pragma("unroll") for (int _i = 0; _i < 2; ++_i) \
;         __builtin_amdgcn_global_load_lds((const unsigned*)((const char*)(gbase) + (voff)[_i]), (PG8_LAS unsigned*)(lds + (bufoff) + ldsw + _i * 8192), 16, 0, 0); } while (0)
; #define PG8_LDA(dst, b, h) do { _Pragma("unroll") for (int m = 0; m < 4; ++m) _Pragma("unroll") for (int k = 0; k < 2; ++k) dst[m][k] = *(const PG8_LAS bf16x8*)(lds + PG8_SA(b, h) + aoff + m * 2048 + k * 1024); } while (0)
; #define PG8_LDB(dst, b, h) do { _Pragma("unroll") for (int n = 0; n < 2; ++n) _Pragma("unroll") for (int k = 0; k < 2; ++k) dst[n][k] = *(const PG8_LAS bf16x8*)(lds + PG8_SB(b, h) + boff + n * 2048 + k * 1024); } while (0)
; #define PG8_MMA(ai, bj, At, Bt) do { __builtin_amdgcn_s_setprio(1); _Pragma("unroll") for (int m = 0; m < 4; ++m) _Pragma("unroll") for (int n = 0; n < 2; ++n) _Pragma("unroll") for (int k = 0; k < 2; ++k) \
;         acc[ai][bj][m][n] = __builtin_amdgcn_mfma_f32_16x16x32_bf16(Bt[n][k], At[m][k], acc[ai][bj][m][n], 0, 0, 0); __builtin_amdgcn_s_setprio(0); } while (0)
; #define PG8_WAIT_V(n) asm volatile("s_waitcnt vmcnt(" #n ")" ::: "memory")
; #define PG8_WAIT_L(n) asm volatile("s_waitcnt lgkmcnt(" #n ")" ::: "memory")
; #define PG8_BAR __builtin_amdgcn_s_barrier()
; #define PG8_SCHED __builtin_amdgcn_sched_barrier(0)
; template <class Epi, class Sched, bool ALIGN_EPI = false, bool SP2 = false>
; __device__ __forceinline__ void gemm_phase(PG8_LAS unsigned char* lds, const Gemm g, const Sched& S, const Epi& E, const int wid_in) {
;     ...
;             PG8_LDB(B0, 0, 0); PG8_LDB(B1, 0, 1); PG8_SCHED; PG8_LDA(At, 0, 0); PG8_STAGE(PG8_SA(1, 1), a1 + hstepA, voffA);
;             PG8_WAIT_V(8); PG8_WAIT_L(0); PG8_BAR; PG8_MMA(0, 0, At, B0); PG8_MMA(0, 1, At, B1); PG8_BAR; PG8_SCHED;
;             PG8_LDA(At, 0, 1); PG8_STAGE(PG8_SB(0, 0), b2, voffB); PG8_STAGE(PG8_SB(0, 1), b2 + hstep, voffB); PG8_STAGE(PG8_SA(0, 0), a2, voffA);
;             PG8_WAIT_V(8); PG8_WAIT_L(0); PG8_BAR; PG8_MMA(1, 0, At, B0); PG8_MMA(1, 1, At, B1); PG8_BAR; PG8_SCHED;
.LBB0_375:
	s_add_u32 s0, s26, 0x100
	s_addc_u32 s1, s27, 0
	s_add_i32 s51, 0, 0x10000
	s_cmp_eq_u32 s50, 28
	s_cselect_b32 s11, s23, s1
	s_cselect_b32 s10, s22, s0
	v_add_u32_e32 v145, s51, v147
	s_cselect_b32 s3, s21, s29
	s_cselect_b32 s2, s49, s28
	s_add_i32 s52, 0, 0x14000
	ds_read_b128 v[166:169], v145
	ds_read_b128 v[174:177], v145 offset:1024
	ds_read_b128 v[178:181], v145 offset:2048
	ds_read_b128 v[182:185], v145 offset:3072
	v_add_u32_e32 v145, s52, v147
	ds_read_b128 v[186:189], v145
	ds_read_b128 v[202:205], v145 offset:1024
	ds_read_b128 v[206:209], v145 offset:2048
	ds_read_b128 v[210:213], v145 offset:3072
	v_lshl_add_u64 v[152:153], s[26:27], 0, v[140:141]
	s_add_i32 m0, s38, 0xc000
	ds_read_b128 v[214:217], v150
	ds_read_b128 v[218:221], v150 offset:1024
	ds_read_b128 v[222:225], v150 offset:2048
	ds_read_b128 v[226:229], v150 offset:3072
	ds_read_b128 v[230:233], v150 offset:4096
	ds_read_b128 v[234:237], v150 offset:5120
	ds_read_b128 v[238:241], v150 offset:6144
	ds_read_b128 v[242:245], v150 offset:7168
	global_load_lds_dwordx4 v[152:153], off
	v_lshl_add_u64 v[152:153], s[26:27], 0, v[142:143]
	s_add_i32 m0, s38, 0xe000
	s_nop 0
	global_load_lds_dwordx4 v[152:153], off
	s_waitcnt lgkmcnt(0)
	s_setprio 1
	s_waitcnt lgkmcnt(0)
	v_mfma_f32_16x16x32_bf16 v[118:121], v[166:169], v[214:217], v[118:121]
	v_mfma_f32_16x16x32_bf16 v[114:117], v[178:181], v[214:217], v[114:117]
	v_mfma_f32_16x16x32_bf16 v[98:101], v[166:169], v[222:225], v[98:101]
	v_mfma_f32_16x16x32_bf16 v[106:109], v[178:181], v[222:225], v[106:109]
	s_waitcnt vmcnt(8)
	s_barrier
	v_mfma_f32_16x16x32_bf16 v[82:85], v[166:169], v[230:233], v[82:85]
	v_mfma_f32_16x16x32_bf16 v[90:93], v[178:181], v[230:233], v[90:93]
	v_mfma_f32_16x16x32_bf16 v[74:77], v[166:169], v[238:241], v[74:77]
	v_mfma_f32_16x16x32_bf16 v[66:69], v[178:181], v[238:241], v[66:69]
	v_mfma_f32_16x16x32_bf16 v[118:121], v[174:177], v[218:221], v[118:121]
	v_mfma_f32_16x16x32_bf16 v[114:117], v[182:185], v[218:221], v[114:117]
	v_mfma_f32_16x16x32_bf16 v[98:101], v[174:177], v[226:229], v[98:101]
	v_mfma_f32_16x16x32_bf16 v[106:109], v[182:185], v[226:229], v[106:109]
	v_mfma_f32_16x16x32_bf16 v[82:85], v[174:177], v[234:237], v[82:85]
	v_mfma_f32_16x16x32_bf16 v[90:93], v[182:185], v[234:237], v[90:93]
	v_mfma_f32_16x16x32_bf16 v[74:77], v[174:177], v[242:245], v[74:77]
	v_mfma_f32_16x16x32_bf16 v[66:69], v[182:185], v[242:245], v[66:69]
	s_setprio 0
	s_setprio 1
	v_mfma_f32_16x16x32_bf16 v[122:125], v[186:189], v[214:217], v[122:125]
	v_mfma_f32_16x16x32_bf16 v[126:129], v[206:209], v[214:217], v[126:129]
	v_mfma_f32_16x16x32_bf16 v[102:105], v[186:189], v[222:225], v[102:105]
	v_mfma_f32_16x16x32_bf16 v[110:113], v[206:209], v[222:225], v[110:113]
	v_mfma_f32_16x16x32_bf16 v[86:89], v[186:189], v[230:233], v[86:89]
	v_mfma_f32_16x16x32_bf16 v[94:97], v[206:209], v[230:233], v[94:97]
	v_mfma_f32_16x16x32_bf16 v[70:73], v[186:189], v[238:241], v[70:73]
	v_mfma_f32_16x16x32_bf16 v[78:81], v[206:209], v[238:241], v[78:81]
	v_mfma_f32_16x16x32_bf16 v[122:125], v[202:205], v[218:221], v[122:125]
	v_mfma_f32_16x16x32_bf16 v[126:129], v[210:213], v[218:221], v[126:129]
	v_mfma_f32_16x16x32_bf16 v[102:105], v[202:205], v[226:229], v[102:105]
	v_mfma_f32_16x16x32_bf16 v[110:113], v[210:213], v[226:229], v[110:113]
	v_mfma_f32_16x16x32_bf16 v[86:89], v[202:205], v[234:237], v[86:89]
	v_mfma_f32_16x16x32_bf16 v[94:97], v[210:213], v[234:237], v[94:97]
	v_mfma_f32_16x16x32_bf16 v[70:73], v[202:205], v[242:245], v[70:73]
	v_mfma_f32_16x16x32_bf16 v[78:81], v[210:213], v[242:245], v[78:81]
	s_setprio 0
	s_barrier
	s_add_i32 s26, s51, s37
	v_lshl_add_u64 v[152:153], s[2:3], 0, v[134:135]
	s_mov_b32 m0, s26
	ds_read_b128 v[214:217], v150 offset:16384
	ds_read_b128 v[218:221], v150 offset:17408
	ds_read_b128 v[222:225], v150 offset:18432
	ds_read_b128 v[226:229], v150 offset:19456
	ds_read_b128 v[230:233], v150 offset:20480
	ds_read_b128 v[234:237], v150 offset:21504
	ds_read_b128 v[238:241], v150 offset:22528
	ds_read_b128 v[242:245], v150 offset:23552
	global_load_lds_dwordx4 v[152:153], off
	s_add_i32 m0, s26, 0x2000
	s_add_u32 s26, s2, 0x80000
	v_lshl_add_u64 v[170:171], s[2:3], 0, v[130:131]
	s_addc_u32 s27, s3, 0
	s_add_i32 s51, s52, s37
	global_load_lds_dwordx4 v[170:171], off
	v_lshl_add_u64 v[190:191], s[26:27], 0, v[134:135]
	s_mov_b32 m0, s51
	v_lshl_add_u64 v[246:247], s[10:11], 0, v[132:133]
	global_load_lds_dwordx4 v[190:191], off
	v_lshl_add_u64 v[190:191], s[26:27], 0, v[130:131]
	s_add_i32 m0, s51, 0x2000
	s_nop 0
	global_load_lds_dwordx4 v[190:191], off
	v_lshl_add_u64 v[190:191], s[10:11], 0, v[136:137]
	s_mov_b32 m0, s38
	s_nop 0
	global_load_lds_dwordx4 v[190:191], off
	s_mov_b32 m0, s39
	s_nop 0
	global_load_lds_dwordx4 v[246:247], off
	s_waitcnt lgkmcnt(0)
	s_setprio 1
	s_waitcnt lgkmcnt(0)
	v_mfma_f32_16x16x32_bf16 v[34:37], v[166:169], v[214:217], v[34:37]
	v_mfma_f32_16x16x32_bf16 v[46:49], v[178:181], v[214:217], v[46:49]
	v_mfma_f32_16x16x32_bf16 v[10:13], v[166:169], v[222:225], v[10:13]
	v_mfma_f32_16x16x32_bf16 v[6:9], v[178:181], v[222:225], v[6:9]
	s_waitcnt vmcnt(8)
	s_barrier
; #define PG8_STAGE(bufoff, gbase, voff) do { _Pragma("unroll") for (int _i = 0; _i < 2; ++_i) \
;         __builtin_amdgcn_global_load_lds((const unsigned*)((const char*)(gbase) + (voff)[_i]), (PG8_LAS unsigned*)(lds + (bufoff) + ldsw + _i * 8192), 16, 0, 0); } while (0)
; #define PG8_LDA(dst, b, h) do { _Pragma("unroll") for (int m = 0; m < 4; ++m) _Pragma("unroll") for (int k = 0; k < 2; ++k) dst[m][k] = *(const PG8_LAS bf16x8*)(lds + PG8_SA(b, h) + aoff + m * 2048 + k * 1024); } while (0)
; #define PG8_LDB(dst, b, h) do { _Pragma("unroll") for (int n = 0; n < 2; ++n) _Pragma("unroll") for (int k = 0; k < 2; ++k) dst[n][k] = *(const PG8_LAS bf16x8*)(lds + PG8_SB(b, h) + boff + n * 2048 + k * 1024); } while (0)
; #define PG8_MMA(ai, bj, At, Bt) do { __builtin_amdgcn_s_setprio(1); _Pragma("unroll") for (int m = 0; m < 4; ++m) _Pragma("unroll") for (int n = 0; n < 2; ++n) _Pragma("unroll") for (int k = 0; k < 2; ++k) \
;         acc[ai][bj][m][n] = __builtin_amdgcn_mfma_f32_16x16x32_bf16(Bt[n][k], At[m][k], acc[ai][bj][m][n], 0, 0, 0); __builtin_amdgcn_s_setprio(0); } while (0)
; #define PG8_WAIT_V(n) asm volatile("s_waitcnt vmcnt(" #n ")" ::: "memory")
; #define PG8_WAIT_L(n) asm volatile("s_waitcnt lgkmcnt(" #n ")" ::: "memory")
; #define PG8_BAR __builtin_amdgcn_s_barrier()
; #define PG8_SCHED __builtin_amdgcn_sched_barrier(0)
; template <class Epi, class Sched, bool ALIGN_EPI = false, bool SP2 = false>
; __device__ __forceinline__ void gemm_phase(PG8_LAS unsigned char* lds, const Gemm g, const Sched& S, const Epi& E, const int wid_in) {
;     ...
;             PG8_WAIT_V(8); PG8_WAIT_L(0); PG8_BAR; PG8_MMA(1, 0, At, B0); PG8_MMA(1, 1, At, B1); PG8_BAR; PG8_SCHED;
;             PG8_LDB(B0, 1, 0); PG8_LDB(B1, 1, 1); PG8_SCHED; PG8_LDA(At, 1, 0); PG8_STAGE(PG8_SA(0, 1), a2 + hstepA, voffA);
;             PG8_WAIT_V(8); PG8_WAIT_L(0); PG8_BAR; PG8_MMA(0, 0, At, B0); PG8_MMA(0, 1, At, B1); PG8_BAR; PG8_SCHED;
	v_mfma_f32_16x16x32_bf16 v[42:45], v[166:169], v[230:233], v[42:45]
	v_mfma_f32_16x16x32_bf16 v[58:61], v[178:181], v[230:233], v[58:61]
	v_mfma_f32_16x16x32_bf16 v[22:25], v[166:169], v[238:241], v[22:25]
	v_mfma_f32_16x16x32_bf16 v[2:5], v[178:181], v[238:241], v[2:5]
	v_mfma_f32_16x16x32_bf16 v[34:37], v[174:177], v[218:221], v[34:37]
	v_mfma_f32_16x16x32_bf16 v[46:49], v[182:185], v[218:221], v[46:49]
	v_mfma_f32_16x16x32_bf16 v[10:13], v[174:177], v[226:229], v[10:13]
	v_mfma_f32_16x16x32_bf16 v[6:9], v[182:185], v[226:229], v[6:9]
	v_mfma_f32_16x16x32_bf16 v[42:45], v[174:177], v[234:237], v[42:45]
	v_mfma_f32_16x16x32_bf16 v[58:61], v[182:185], v[234:237], v[58:61]
	v_mfma_f32_16x16x32_bf16 v[22:25], v[174:177], v[242:245], v[22:25]
	v_mfma_f32_16x16x32_bf16 v[2:5], v[182:185], v[242:245], v[2:5]
	s_setprio 0
	s_setprio 1
	v_mfma_f32_16x16x32_bf16 v[38:41], v[186:189], v[214:217], v[38:41]
	v_mfma_f32_16x16x32_bf16 v[54:57], v[206:209], v[214:217], v[54:57]
	v_mfma_f32_16x16x32_bf16 v[14:17], v[186:189], v[222:225], v[14:17]
	v_mfma_f32_16x16x32_bf16 v[26:29], v[206:209], v[222:225], v[26:29]
	v_mfma_f32_16x16x32_bf16 v[50:53], v[186:189], v[230:233], v[50:53]
	v_mfma_f32_16x16x32_bf16 v[62:65], v[206:209], v[230:233], v[62:65]
	v_mfma_f32_16x16x32_bf16 v[18:21], v[186:189], v[238:241], v[18:21]
	v_mfma_f32_16x16x32_bf16 v[30:33], v[206:209], v[238:241], v[30:33]
	v_mfma_f32_16x16x32_bf16 v[38:41], v[202:205], v[218:221], v[38:41]
	v_mfma_f32_16x16x32_bf16 v[54:57], v[210:213], v[218:221], v[54:57]
	v_mfma_f32_16x16x32_bf16 v[14:17], v[202:205], v[226:229], v[14:17]
	v_mfma_f32_16x16x32_bf16 v[26:29], v[210:213], v[226:229], v[26:29]
	v_mfma_f32_16x16x32_bf16 v[50:53], v[202:205], v[234:237], v[50:53]
	v_mfma_f32_16x16x32_bf16 v[62:65], v[210:213], v[234:237], v[62:65]
	v_mfma_f32_16x16x32_bf16 v[18:21], v[202:205], v[242:245], v[18:21]
	v_mfma_f32_16x16x32_bf16 v[30:33], v[210:213], v[242:245], v[30:33]
	s_setprio 0
	s_barrier
	s_add_i32 s26, 0, 0x18000
	v_add_u32_e32 v145, s26, v147
	s_add_i32 s27, 0, 0x1c000
	ds_read_b128 v[166:169], v145
	ds_read_b128 v[174:177], v145 offset:1024
	ds_read_b128 v[178:181], v145 offset:2048
	ds_read_b128 v[182:185], v145 offset:3072
	v_add_u32_e32 v145, s27, v147
	ds_read_b128 v[186:189], v145
	ds_read_b128 v[202:205], v145 offset:1024
	ds_read_b128 v[206:209], v145 offset:2048
	ds_read_b128 v[210:213], v145 offset:3072
	s_add_u32 s10, s10, 0x140000
	s_addc_u32 s11, s11, 0
	s_mov_b32 m0, s40
	v_lshl_add_u64 v[248:249], s[10:11], 0, v[136:137]
	ds_read_b128 v[214:217], v150 offset:32768
	ds_read_b128 v[218:221], v150 offset:33792
	ds_read_b128 v[222:225], v150 offset:34816
	ds_read_b128 v[226:229], v150 offset:35840
	ds_read_b128 v[230:233], v150 offset:36864
	ds_read_b128 v[234:237], v150 offset:37888
	ds_read_b128 v[238:241], v150 offset:38912
	ds_read_b128 v[242:245], v150 offset:39936
	global_load_lds_dwordx4 v[248:249], off
	v_lshl_add_u64 v[248:249], s[10:11], 0, v[132:133]
	s_mov_b32 m0, s41
	s_nop 0
	global_load_lds_dwordx4 v[248:249], off
	s_waitcnt lgkmcnt(0)
	s_setprio 1
	s_waitcnt lgkmcnt(0)
	v_mfma_f32_16x16x32_bf16 v[118:121], v[166:169], v[214:217], v[118:121]
	v_mfma_f32_16x16x32_bf16 v[114:117], v[178:181], v[214:217], v[114:117]
	v_mfma_f32_16x16x32_bf16 v[98:101], v[166:169], v[222:225], v[98:101]
	v_mfma_f32_16x16x32_bf16 v[106:109], v[178:181], v[222:225], v[106:109]
	s_waitcnt vmcnt(8)
	s_barrier
	v_mfma_f32_16x16x32_bf16 v[82:85], v[166:169], v[230:233], v[82:85]
	v_mfma_f32_16x16x32_bf16 v[90:93], v[178:181], v[230:233], v[90:93]
	v_mfma_f32_16x16x32_bf16 v[74:77], v[166:169], v[238:241], v[74:77]
	v_mfma_f32_16x16x32_bf16 v[66:69], v[178:181], v[238:241], v[66:69]
	v_mfma_f32_16x16x32_bf16 v[118:121], v[174:177], v[218:221], v[118:121]
	v_mfma_f32_16x16x32_bf16 v[114:117], v[182:185], v[218:221], v[114:117]
	v_mfma_f32_16x16x32_bf16 v[98:101], v[174:177], v[226:229], v[98:101]
	v_mfma_f32_16x16x32_bf16 v[106:109], v[182:185], v[226:229], v[106:109]
	v_mfma_f32_16x16x32_bf16 v[82:85], v[174:177], v[234:237], v[82:85]
	v_mfma_f32_16x16x32_bf16 v[90:93], v[182:185], v[234:237], v[90:93]
	v_mfma_f32_16x16x32_bf16 v[74:77], v[174:177], v[242:245], v[74:77]
	v_mfma_f32_16x16x32_bf16 v[66:69], v[182:185], v[242:245], v[66:69]
	s_setprio 0
	s_setprio 1
	v_mfma_f32_16x16x32_bf16 v[122:125], v[186:189], v[214:217], v[122:125]
	v_mfma_f32_16x16x32_bf16 v[126:129], v[206:209], v[214:217], v[126:129]
	v_mfma_f32_16x16x32_bf16 v[102:105], v[186:189], v[222:225], v[102:105]
	v_mfma_f32_16x16x32_bf16 v[110:113], v[206:209], v[222:225], v[110:113]
	v_mfma_f32_16x16x32_bf16 v[86:89], v[186:189], v[230:233], v[86:89]
	v_mfma_f32_16x16x32_bf16 v[94:97], v[206:209], v[230:233], v[94:97]
	v_mfma_f32_16x16x32_bf16 v[70:73], v[186:189], v[238:241], v[70:73]
	v_mfma_f32_16x16x32_bf16 v[78:81], v[206:209], v[238:241], v[78:81]
	v_mfma_f32_16x16x32_bf16 v[122:125], v[202:205], v[218:221], v[122:125]
	v_mfma_f32_16x16x32_bf16 v[126:129], v[210:213], v[218:221], v[126:129]
	v_mfma_f32_16x16x32_bf16 v[102:105], v[202:205], v[226:229], v[102:105]
	v_mfma_f32_16x16x32_bf16 v[110:113], v[210:213], v[226:229], v[110:113]
	v_mfma_f32_16x16x32_bf16 v[86:89], v[202:205], v[234:237], v[86:89]
	v_mfma_f32_16x16x32_bf16 v[94:97], v[210:213], v[234:237], v[94:97]
	v_mfma_f32_16x16x32_bf16 v[70:73], v[202:205], v[242:245], v[70:73]
	v_mfma_f32_16x16x32_bf16 v[78:81], v[210:213], v[242:245], v[78:81]
	s_setprio 0
	s_barrier
; #define PG8_STAGE(bufoff, gbase, voff) do { _Pragma("unroll") for (int _i = 0; _i < 2; ++_i) \
;         __builtin_amdgcn_global_load_lds((const unsigned*)((const char*)(gbase) + (voff)[_i]), (PG8_LAS unsigned*)(lds + (bufoff) + ldsw + _i * 8192), 16, 0, 0); } while (0)
; #define PG8_LDA(dst, b, h) do { _Pragma("unroll") for (int m = 0; m < 4; ++m) _Pragma("unroll") for (int k = 0; k < 2; ++k) dst[m][k] = *(const PG8_LAS bf16x8*)(lds + PG8_SA(b, h) + aoff + m * 2048 + k * 1024); } while (0)
; #define PG8_MMA(ai, bj, At, Bt) do { __builtin_amdgcn_s_setprio(1); _Pragma("unroll") for (int m = 0; m < 4; ++m) _Pragma("unroll") for (int n = 0; n < 2; ++n) _Pragma("unroll") for (int k = 0; k < 2; ++k) \
;         acc[ai][bj][m][n] = __builtin_amdgcn_mfma_f32_16x16x32_bf16(Bt[n][k], At[m][k], acc[ai][bj][m][n], 0, 0, 0); __builtin_amdgcn_s_setprio(0); } while (0)
; #define PG8_WAIT_V(n) asm volatile("s_waitcnt vmcnt(" #n ")" ::: "memory")
; #define PG8_WAIT_L(n) asm volatile("s_waitcnt lgkmcnt(" #n ")" ::: "memory")
; #define PG8_BAR __builtin_amdgcn_s_barrier()
; #define PG8_SCHED __builtin_amdgcn_sched_barrier(0)
; template <class Epi, class Sched, bool ALIGN_EPI = false, bool SP2 = false>
; __device__ __forceinline__ void gemm_phase(PG8_LAS unsigned char* lds, const Gemm g, const Sched& S, const Epi& E, const int wid_in) {
;     ...
;             PG8_LDA(At, 1, 1); PG8_STAGE(PG8_SB(1, 0), b3, voffB); PG8_STAGE(PG8_SB(1, 1), b3 + hstep, voffB); PG8_STAGE(PG8_SA(1, 0), a3, voffA);
;             PG8_WAIT_V(8); PG8_WAIT_L(0); PG8_BAR; PG8_MMA(1, 0, At, B0); PG8_MMA(1, 1, At, B1); PG8_BAR; PG8_SCHED;
;     ...
;         if constexpr (ALIGN_EPI) { if (wr == 0) PG8_BAR; }
	s_add_i32 s10, s26, s37
	v_lshl_add_u64 v[152:153], v[152:153], 0, s[98:99]
	s_mov_b32 m0, s10
	ds_read_b128 v[214:217], v150 offset:49152
	ds_read_b128 v[218:221], v150 offset:50176
	ds_read_b128 v[222:225], v150 offset:51200
	ds_read_b128 v[226:229], v150 offset:52224
	ds_read_b128 v[230:233], v150 offset:53248
	ds_read_b128 v[234:237], v150 offset:54272
	ds_read_b128 v[238:241], v150 offset:55296
	ds_read_b128 v[242:245], v150 offset:56320
	global_load_lds_dwordx4 v[152:153], off
	s_add_i32 m0, s10, 0x2000
	s_add_u32 s2, s2, 0x80080
	v_lshl_add_u64 v[152:153], v[170:171], 0, s[98:99]
	s_addc_u32 s3, s3, 0
	s_add_i32 s10, s27, s37
	global_load_lds_dwordx4 v[152:153], off
	v_lshl_add_u64 v[152:153], s[2:3], 0, v[134:135]
	s_mov_b32 m0, s10
	s_nop 0
	global_load_lds_dwordx4 v[152:153], off
	v_lshl_add_u64 v[152:153], s[2:3], 0, v[130:131]
	s_add_i32 m0, s10, 0x2000
	s_nop 0
	global_load_lds_dwordx4 v[152:153], off
	v_lshl_add_u64 v[152:153], v[190:191], 0, s[98:99]
	s_mov_b32 m0, s44
	s_nop 0
	global_load_lds_dwordx4 v[152:153], off
	v_lshl_add_u64 v[152:153], v[246:247], 0, s[98:99]
	s_mov_b32 m0, s45
	s_nop 0
	global_load_lds_dwordx4 v[152:153], off
	s_waitcnt lgkmcnt(0)
	s_setprio 1
	s_waitcnt lgkmcnt(0)
	v_mfma_f32_16x16x32_bf16 v[34:37], v[166:169], v[214:217], v[34:37]
	v_mfma_f32_16x16x32_bf16 v[46:49], v[178:181], v[214:217], v[46:49]
	v_mfma_f32_16x16x32_bf16 v[10:13], v[166:169], v[222:225], v[10:13]
	v_mfma_f32_16x16x32_bf16 v[6:9], v[178:181], v[222:225], v[6:9]
	s_waitcnt vmcnt(8)
	s_barrier
	v_mfma_f32_16x16x32_bf16 v[42:45], v[166:169], v[230:233], v[42:45]
	v_mfma_f32_16x16x32_bf16 v[58:61], v[178:181], v[230:233], v[58:61]
	v_mfma_f32_16x16x32_bf16 v[22:25], v[166:169], v[238:241], v[22:25]
	v_mfma_f32_16x16x32_bf16 v[2:5], v[178:181], v[238:241], v[2:5]
	v_mfma_f32_16x16x32_bf16 v[34:37], v[174:177], v[218:221], v[34:37]
	v_mfma_f32_16x16x32_bf16 v[46:49], v[182:185], v[218:221], v[46:49]
	v_mfma_f32_16x16x32_bf16 v[10:13], v[174:177], v[226:229], v[10:13]
	v_mfma_f32_16x16x32_bf16 v[6:9], v[182:185], v[226:229], v[6:9]
	v_mfma_f32_16x16x32_bf16 v[42:45], v[174:177], v[234:237], v[42:45]
	v_mfma_f32_16x16x32_bf16 v[58:61], v[182:185], v[234:237], v[58:61]
	v_mfma_f32_16x16x32_bf16 v[22:25], v[174:177], v[242:245], v[22:25]
	v_mfma_f32_16x16x32_bf16 v[2:5], v[182:185], v[242:245], v[2:5]
	s_setprio 0
	s_setprio 1
	v_mfma_f32_16x16x32_bf16 v[38:41], v[186:189], v[214:217], v[38:41]
	v_mfma_f32_16x16x32_bf16 v[54:57], v[206:209], v[214:217], v[54:57]
	v_mfma_f32_16x16x32_bf16 v[14:17], v[186:189], v[222:225], v[14:17]
	v_mfma_f32_16x16x32_bf16 v[26:29], v[206:209], v[222:225], v[26:29]
	v_mfma_f32_16x16x32_bf16 v[50:53], v[186:189], v[230:233], v[50:53]
	v_mfma_f32_16x16x32_bf16 v[62:65], v[206:209], v[230:233], v[62:65]
	v_mfma_f32_16x16x32_bf16 v[18:21], v[186:189], v[238:241], v[18:21]
	v_mfma_f32_16x16x32_bf16 v[30:33], v[206:209], v[238:241], v[30:33]
	v_mfma_f32_16x16x32_bf16 v[38:41], v[202:205], v[218:221], v[38:41]
	v_mfma_f32_16x16x32_bf16 v[54:57], v[210:213], v[218:221], v[54:57]
	v_mfma_f32_16x16x32_bf16 v[14:17], v[202:205], v[226:229], v[14:17]
	v_mfma_f32_16x16x32_bf16 v[26:29], v[210:213], v[226:229], v[26:29]
	v_mfma_f32_16x16x32_bf16 v[50:53], v[202:205], v[234:237], v[50:53]
	v_mfma_f32_16x16x32_bf16 v[62:65], v[210:213], v[234:237], v[62:65]
	v_mfma_f32_16x16x32_bf16 v[18:21], v[202:205], v[242:245], v[18:21]
	v_mfma_f32_16x16x32_bf16 v[30:33], v[210:213], v[242:245], v[30:33]
	s_setprio 0
	s_barrier
	s_add_i32 s50, s50, 2
	s_add_u32 s28, s28, 0x100
	s_addc_u32 s29, s29, 0
	s_cmp_gt_u32 s50, 29
	s_mov_b64 s[26:27], s[0:1]
	s_cbranch_scc0 .LBB0_375
	s_and_b64 vcc, exec, s[16:17]
	s_cbranch_vccz .LBB0_378
	s_barrier

; #define PG8_STAGE(bufoff, gbase, voff) do { _Pragma("unroll") for (int _i = 0; _i < 2; ++_i) \
;         __builtin_amdgcn_global_load_lds((const unsigned*)((const char*)(gbase) + (voff)[_i]), (PG8_LAS unsigned*)(lds + (bufoff) + ldsw + _i * 8192), 16, 0, 0); } while (0)
; #define PG8_LDA(dst, b, h) do { _Pragma("unroll") for (int m = 0; m < 4; ++m) _Pragma("unroll") for (int k = 0; k < 2; ++k) dst[m][k] = *(const PG8_LAS bf16x8*)(lds + PG8_SA(b, h) + aoff + m * 2048 + k * 1024); } while (0)
; #define PG8_LDB(dst, b, h) do { _Pragma("unroll") for (int n = 0; n < 2; ++n) _Pragma("unroll") for (int k = 0; k < 2; ++k) dst[n][k] = *(const PG8_LAS bf16x8*)(lds + PG8_SB(b, h) + boff + n * 2048 + k * 1024); } while (0)
; #define PG8_MMA(ai, bj, At, Bt) do { __builtin_amdgcn_s_setprio(1); _Pragma("unroll") for (int m = 0; m < 4; ++m) _Pragma("unroll") for (int n = 0; n < 2; ++n) _Pragma("unroll") for (int k = 0; k < 2; ++k) \
;         acc[ai][bj][m][n] = __builtin_amdgcn_mfma_f32_16x16x32_bf16(Bt[n][k], At[m][k], acc[ai][bj][m][n], 0, 0, 0); __builtin_amdgcn_s_setprio(0); } while (0)
; #define PG8_WAIT_V(n) asm volatile("s_waitcnt vmcnt(" #n ")" ::: "memory")
; #define PG8_WAIT_L(n) asm volatile("s_waitcnt lgkmcnt(" #n ")" ::: "memory")
; template <class Epi, class Sched, bool ALIGN_EPI = false, bool SP2 = false>
; __device__ __forceinline__ void gemm_phase(PG8_LAS unsigned char* lds, const Gemm g, const Sched& S, const Epi& E, const int wid_in) {
;     ...
;             const bool last = (t == nt - 2);
;             const char* a1 = cA + (size_t)(t + 1) * kstep;
;             const char* a2 = last ? nA : cA + (size_t)(t + 2) * kstep; const char* b2 = last ? nB : cB + (size_t)(t + 2) * kstep;
;             const char* a3 = a2 + kstep; const char* b3 = b2 + kstep;
;             if (last && has_next) S.a_ready(nxt);
;             if constexpr (SP2) {
;             PG8_LDB(B0, 0, 0); PG8_LDB(B1, 0, 1); PG8_SCHED; PG8_LDA(At, 0, 0); PG8_STAGE(PG8_SA(1, 1), a1 + hstepA, voffA);
;             PG8_WAIT_V(8); PG8_WAIT_L(0); PG8_BAR; PG8_MMA(0, 0, At, B0); PG8_MMA(0, 1, At, B1); PG8_BAR; PG8_SCHED;
;             PG8_LDA(At, 0, 1); PG8_STAGE(PG8_SB(0, 0), b2, voffB); PG8_STAGE(PG8_SB(0, 1), b2 + hstep, voffB); PG8_STAGE(PG8_SA(0, 0), a2, voffA);
;             PG8_WAIT_V(8); PG8_WAIT_L(0); PG8_BAR; PG8_MMA(1, 0, At, B0); PG8_MMA(1, 1, At, B1); PG8_BAR; PG8_SCHED;
.LBB0_484:
	s_add_u32 s0, s24, 0xfff80080
	s_addc_u32 s1, s25, -1
	s_add_i32 s49, 0, 0x10000
	s_cmp_eq_u32 s48, 28
	s_cselect_b32 s3, s19, s1
	s_cselect_b32 s2, s44, s0
	v_add_u32_e32 v150, s49, v152
	s_cselect_b32 s1, s17, s47
	s_cselect_b32 s0, s45, s46
	s_add_i32 s52, 0, 0x14000
	ds_read_b128 v[142:145], v150
	ds_read_b128 v[146:149], v150 offset:1024
	ds_read_b128 v[168:171], v150 offset:2048
	ds_read_b128 v[174:177], v150 offset:3072
	v_add_u32_e32 v150, s52, v152
	ds_read_b128 v[178:181], v150
	ds_read_b128 v[182:185], v150 offset:1024
	ds_read_b128 v[186:189], v150 offset:2048
	ds_read_b128 v[202:205], v150 offset:3072
	v_lshl_add_u64 v[150:151], s[24:25], 0, v[138:139]
	s_add_i32 m0, s35, 0xc000
	ds_read_b128 v[206:209], v167
	ds_read_b128 v[210:213], v167 offset:1024
	ds_read_b128 v[214:217], v167 offset:2048
	ds_read_b128 v[218:221], v167 offset:3072
	ds_read_b128 v[222:225], v167 offset:4096
	ds_read_b128 v[226:229], v167 offset:5120
	ds_read_b128 v[230:233], v167 offset:6144
	ds_read_b128 v[234:237], v167 offset:7168
	global_load_lds_dwordx4 v[150:151], off
	v_lshl_add_u64 v[150:151], s[24:25], 0, v[140:141]
	s_add_i32 m0, s35, 0xe000
	s_nop 0
	global_load_lds_dwordx4 v[150:151], off
	s_waitcnt lgkmcnt(0)
	s_setprio 1
	s_waitcnt lgkmcnt(0)
	v_mfma_f32_16x16x32_bf16 v[126:129], v[142:145], v[206:209], v[126:129]
	v_mfma_f32_16x16x32_bf16 v[122:125], v[168:171], v[206:209], v[122:125]
	v_mfma_f32_16x16x32_bf16 v[110:113], v[142:145], v[214:217], v[110:113]
	v_mfma_f32_16x16x32_bf16 v[106:109], v[168:171], v[214:217], v[106:109]
	s_waitcnt vmcnt(8)
	s_barrier
	v_mfma_f32_16x16x32_bf16 v[94:97], v[142:145], v[222:225], v[94:97]
	v_mfma_f32_16x16x32_bf16 v[90:93], v[168:171], v[222:225], v[90:93]
	v_mfma_f32_16x16x32_bf16 v[78:81], v[142:145], v[230:233], v[78:81]
	v_mfma_f32_16x16x32_bf16 v[74:77], v[168:171], v[230:233], v[74:77]
	v_mfma_f32_16x16x32_bf16 v[126:129], v[146:149], v[210:213], v[126:129]
	v_mfma_f32_16x16x32_bf16 v[122:125], v[174:177], v[210:213], v[122:125]
	v_mfma_f32_16x16x32_bf16 v[110:113], v[146:149], v[218:221], v[110:113]
	v_mfma_f32_16x16x32_bf16 v[106:109], v[174:177], v[218:221], v[106:109]
	v_mfma_f32_16x16x32_bf16 v[94:97], v[146:149], v[226:229], v[94:97]
	v_mfma_f32_16x16x32_bf16 v[90:93], v[174:177], v[226:229], v[90:93]
	v_mfma_f32_16x16x32_bf16 v[78:81], v[146:149], v[234:237], v[78:81]
	v_mfma_f32_16x16x32_bf16 v[74:77], v[174:177], v[234:237], v[74:77]
	s_setprio 0
	s_setprio 1
	v_mfma_f32_16x16x32_bf16 v[118:121], v[178:181], v[206:209], v[118:121]
	v_mfma_f32_16x16x32_bf16 v[114:117], v[186:189], v[206:209], v[114:117]
	v_mfma_f32_16x16x32_bf16 v[102:105], v[178:181], v[214:217], v[102:105]
	v_mfma_f32_16x16x32_bf16 v[98:101], v[186:189], v[214:217], v[98:101]
	v_mfma_f32_16x16x32_bf16 v[86:89], v[178:181], v[222:225], v[86:89]
	v_mfma_f32_16x16x32_bf16 v[82:85], v[186:189], v[222:225], v[82:85]
	v_mfma_f32_16x16x32_bf16 v[70:73], v[178:181], v[230:233], v[70:73]
	v_mfma_f32_16x16x32_bf16 v[66:69], v[186:189], v[230:233], v[66:69]
	v_mfma_f32_16x16x32_bf16 v[118:121], v[182:185], v[210:213], v[118:121]
	v_mfma_f32_16x16x32_bf16 v[114:117], v[202:205], v[210:213], v[114:117]
	v_mfma_f32_16x16x32_bf16 v[102:105], v[182:185], v[218:221], v[102:105]
	v_mfma_f32_16x16x32_bf16 v[98:101], v[202:205], v[218:221], v[98:101]
	v_mfma_f32_16x16x32_bf16 v[86:89], v[182:185], v[226:229], v[86:89]
	v_mfma_f32_16x16x32_bf16 v[82:85], v[202:205], v[226:229], v[82:85]
	v_mfma_f32_16x16x32_bf16 v[70:73], v[182:185], v[234:237], v[70:73]
	v_mfma_f32_16x16x32_bf16 v[66:69], v[202:205], v[234:237], v[66:69]
	s_setprio 0
	s_barrier
	s_add_i32 s49, s49, s29
	v_lshl_add_u64 v[150:151], s[0:1], 0, v[134:135]
	s_mov_b32 m0, s49
	ds_read_b128 v[206:209], v167 offset:16384
	ds_read_b128 v[210:213], v167 offset:17408
	ds_read_b128 v[214:217], v167 offset:18432
	ds_read_b128 v[218:221], v167 offset:19456
	ds_read_b128 v[222:225], v167 offset:20480
	ds_read_b128 v[226:229], v167 offset:21504
	ds_read_b128 v[230:233], v167 offset:22528
	ds_read_b128 v[234:237], v167 offset:23552
	global_load_lds_dwordx4 v[150:151], off
	s_add_i32 m0, s49, 0x2000
	s_add_u32 s50, s0, 0x80000
	v_lshl_add_u64 v[190:191], s[0:1], 0, v[130:131]
	s_addc_u32 s51, s1, 0
	s_add_i32 s49, s52, s29
	global_load_lds_dwordx4 v[190:191], off
	v_lshl_add_u64 v[238:239], s[50:51], 0, v[134:135]
	s_mov_b32 m0, s49
	v_lshl_add_u64 v[240:241], s[2:3], 0, v[132:133]
	global_load_lds_dwordx4 v[238:239], off
	v_lshl_add_u64 v[238:239], s[50:51], 0, v[130:131]
	s_add_i32 m0, s49, 0x2000
	s_nop 0
	global_load_lds_dwordx4 v[238:239], off
	v_lshl_add_u64 v[238:239], s[2:3], 0, v[136:137]
	s_mov_b32 m0, s35
	s_nop 0
	global_load_lds_dwordx4 v[238:239], off
	s_mov_b32 m0, s36
	s_nop 0
	global_load_lds_dwordx4 v[240:241], off
	s_waitcnt lgkmcnt(0)
	s_setprio 1
	s_waitcnt lgkmcnt(0)
	v_mfma_f32_16x16x32_bf16 v[62:65], v[142:145], v[206:209], v[62:65]
	v_mfma_f32_16x16x32_bf16 v[58:61], v[168:171], v[206:209], v[58:61]
	v_mfma_f32_16x16x32_bf16 v[46:49], v[142:145], v[214:217], v[46:49]
	v_mfma_f32_16x16x32_bf16 v[42:45], v[168:171], v[214:217], v[42:45]
	s_waitcnt vmcnt(8)
	s_barrier
; #define PG8_STAGE(bufoff, gbase, voff) do { _Pragma("unroll") for (int _i = 0; _i < 2; ++_i) \
;         __builtin_amdgcn_global_load_lds((const unsigned*)((const char*)(gbase) + (voff)[_i]), (PG8_LAS unsigned*)(lds + (bufoff) + ldsw + _i * 8192), 16, 0, 0); } while (0)
; #define PG8_LDA(dst, b, h) do { _Pragma("unroll") for (int m = 0; m < 4; ++m) _Pragma("unroll") for (int k = 0; k < 2; ++k) dst[m][k] = *(const PG8_LAS bf16x8*)(lds + PG8_SA(b, h) + aoff + m * 2048 + k * 1024); } while (0)
; #define PG8_LDB(dst, b, h) do { _Pragma("unroll") for (int n = 0; n < 2; ++n) _Pragma("unroll") for (int k = 0; k < 2; ++k) dst[n][k] = *(const PG8_LAS bf16x8*)(lds + PG8_SB(b, h) + boff + n * 2048 + k * 1024); } while (0)
; #define PG8_MMA(ai, bj, At, Bt) do { __builtin_amdgcn_s_setprio(1); _Pragma("unroll") for (int m = 0; m < 4; ++m) _Pragma("unroll") for (int n = 0; n < 2; ++n) _Pragma("unroll") for (int k = 0; k < 2; ++k) \
;         acc[ai][bj][m][n] = __builtin_amdgcn_mfma_f32_16x16x32_bf16(Bt[n][k], At[m][k], acc[ai][bj][m][n], 0, 0, 0); __builtin_amdgcn_s_setprio(0); } while (0)
; #define PG8_WAIT_V(n) asm volatile("s_waitcnt vmcnt(" #n ")" ::: "memory")
; #define PG8_WAIT_L(n) asm volatile("s_waitcnt lgkmcnt(" #n ")" ::: "memory")
; #define PG8_BAR __builtin_amdgcn_s_barrier()
; #define PG8_SCHED __builtin_amdgcn_sched_barrier(0)
; template <class Epi, class Sched, bool ALIGN_EPI = false, bool SP2 = false>
; __device__ __forceinline__ void gemm_phase(PG8_LAS unsigned char* lds, const Gemm g, const Sched& S, const Epi& E, const int wid_in) {
;     ...
;             PG8_WAIT_V(8); PG8_WAIT_L(0); PG8_BAR; PG8_MMA(1, 0, At, B0); PG8_MMA(1, 1, At, B1); PG8_BAR; PG8_SCHED;
;             PG8_LDB(B0, 1, 0); PG8_LDB(B1, 1, 1); PG8_SCHED; PG8_LDA(At, 1, 0); PG8_STAGE(PG8_SA(0, 1), a2 + hstepA, voffA);
;             PG8_WAIT_V(8); PG8_WAIT_L(0); PG8_BAR; PG8_MMA(0, 0, At, B0); PG8_MMA(0, 1, At, B1); PG8_BAR; PG8_SCHED;
	v_mfma_f32_16x16x32_bf16 v[30:33], v[142:145], v[222:225], v[30:33]
	v_mfma_f32_16x16x32_bf16 v[26:29], v[168:171], v[222:225], v[26:29]
	v_mfma_f32_16x16x32_bf16 v[14:17], v[142:145], v[230:233], v[14:17]
	v_mfma_f32_16x16x32_bf16 v[10:13], v[168:171], v[230:233], v[10:13]
	v_mfma_f32_16x16x32_bf16 v[62:65], v[146:149], v[210:213], v[62:65]
	v_mfma_f32_16x16x32_bf16 v[58:61], v[174:177], v[210:213], v[58:61]
	v_mfma_f32_16x16x32_bf16 v[46:49], v[146:149], v[218:221], v[46:49]
	v_mfma_f32_16x16x32_bf16 v[42:45], v[174:177], v[218:221], v[42:45]
	v_mfma_f32_16x16x32_bf16 v[30:33], v[146:149], v[226:229], v[30:33]
	v_mfma_f32_16x16x32_bf16 v[26:29], v[174:177], v[226:229], v[26:29]
	v_mfma_f32_16x16x32_bf16 v[14:17], v[146:149], v[234:237], v[14:17]
	v_mfma_f32_16x16x32_bf16 v[10:13], v[174:177], v[234:237], v[10:13]
	s_setprio 0
	s_setprio 1
	v_mfma_f32_16x16x32_bf16 v[54:57], v[178:181], v[206:209], v[54:57]
	v_mfma_f32_16x16x32_bf16 v[50:53], v[186:189], v[206:209], v[50:53]
	v_mfma_f32_16x16x32_bf16 v[38:41], v[178:181], v[214:217], v[38:41]
	v_mfma_f32_16x16x32_bf16 v[34:37], v[186:189], v[214:217], v[34:37]
	v_mfma_f32_16x16x32_bf16 v[22:25], v[178:181], v[222:225], v[22:25]
	v_mfma_f32_16x16x32_bf16 v[18:21], v[186:189], v[222:225], v[18:21]
	v_mfma_f32_16x16x32_bf16 v[6:9], v[178:181], v[230:233], v[6:9]
	v_mfma_f32_16x16x32_bf16 v[2:5], v[186:189], v[230:233], v[2:5]
	v_mfma_f32_16x16x32_bf16 v[54:57], v[182:185], v[210:213], v[54:57]
	v_mfma_f32_16x16x32_bf16 v[50:53], v[202:205], v[210:213], v[50:53]
	v_mfma_f32_16x16x32_bf16 v[38:41], v[182:185], v[218:221], v[38:41]
	v_mfma_f32_16x16x32_bf16 v[34:37], v[202:205], v[218:221], v[34:37]
	v_mfma_f32_16x16x32_bf16 v[22:25], v[182:185], v[226:229], v[22:25]
	v_mfma_f32_16x16x32_bf16 v[18:21], v[202:205], v[226:229], v[18:21]
	v_mfma_f32_16x16x32_bf16 v[6:9], v[182:185], v[234:237], v[6:9]
	v_mfma_f32_16x16x32_bf16 v[2:5], v[202:205], v[234:237], v[2:5]
	s_setprio 0
	s_barrier
	s_add_i32 s49, 0, 0x18000
	s_add_i32 s50, 0, 0x1c000
	v_add_u32_e32 v174, s49, v152
	v_add_u32_e32 v202, s50, v152
	ds_read_b128 v[142:145], v174
	ds_read_b128 v[146:149], v174 offset:1024
	ds_read_b128 v[168:171], v174 offset:2048
	ds_read_b128 v[174:177], v174 offset:3072
	ds_read_b128 v[178:181], v202
	ds_read_b128 v[182:185], v202 offset:1024
	ds_read_b128 v[186:189], v202 offset:2048
	ds_read_b128 v[202:205], v202 offset:3072
	s_add_u32 s2, s2, 0x80000
	s_addc_u32 s3, s3, 0
	s_mov_b32 m0, s37
	v_lshl_add_u64 v[242:243], s[2:3], 0, v[136:137]
	ds_read_b128 v[206:209], v167 offset:32768
	ds_read_b128 v[210:213], v167 offset:33792
	ds_read_b128 v[214:217], v167 offset:34816
	ds_read_b128 v[218:221], v167 offset:35840
	ds_read_b128 v[222:225], v167 offset:36864
	ds_read_b128 v[226:229], v167 offset:37888
	ds_read_b128 v[230:233], v167 offset:38912
	ds_read_b128 v[234:237], v167 offset:39936
	global_load_lds_dwordx4 v[242:243], off
	v_lshl_add_u64 v[242:243], s[2:3], 0, v[132:133]
	s_mov_b32 m0, s38
	s_nop 0
	global_load_lds_dwordx4 v[242:243], off
	s_waitcnt lgkmcnt(0)
	s_setprio 1
	s_waitcnt lgkmcnt(0)
	v_mfma_f32_16x16x32_bf16 v[126:129], v[142:145], v[206:209], v[126:129]
	v_mfma_f32_16x16x32_bf16 v[122:125], v[168:171], v[206:209], v[122:125]
	v_mfma_f32_16x16x32_bf16 v[110:113], v[142:145], v[214:217], v[110:113]
	v_mfma_f32_16x16x32_bf16 v[106:109], v[168:171], v[214:217], v[106:109]
	s_waitcnt vmcnt(8)
	s_barrier
	v_mfma_f32_16x16x32_bf16 v[94:97], v[142:145], v[222:225], v[94:97]
	v_mfma_f32_16x16x32_bf16 v[90:93], v[168:171], v[222:225], v[90:93]
	v_mfma_f32_16x16x32_bf16 v[78:81], v[142:145], v[230:233], v[78:81]
	v_mfma_f32_16x16x32_bf16 v[74:77], v[168:171], v[230:233], v[74:77]
	v_mfma_f32_16x16x32_bf16 v[126:129], v[146:149], v[210:213], v[126:129]
	v_mfma_f32_16x16x32_bf16 v[122:125], v[174:177], v[210:213], v[122:125]
	v_mfma_f32_16x16x32_bf16 v[110:113], v[146:149], v[218:221], v[110:113]
	v_mfma_f32_16x16x32_bf16 v[106:109], v[174:177], v[218:221], v[106:109]
	v_mfma_f32_16x16x32_bf16 v[94:97], v[146:149], v[226:229], v[94:97]
	v_mfma_f32_16x16x32_bf16 v[90:93], v[174:177], v[226:229], v[90:93]
	v_mfma_f32_16x16x32_bf16 v[78:81], v[146:149], v[234:237], v[78:81]
	v_mfma_f32_16x16x32_bf16 v[74:77], v[174:177], v[234:237], v[74:77]
	s_setprio 0
	s_setprio 1
	v_mfma_f32_16x16x32_bf16 v[118:121], v[178:181], v[206:209], v[118:121]
	v_mfma_f32_16x16x32_bf16 v[114:117], v[186:189], v[206:209], v[114:117]
	v_mfma_f32_16x16x32_bf16 v[102:105], v[178:181], v[214:217], v[102:105]
	v_mfma_f32_16x16x32_bf16 v[98:101], v[186:189], v[214:217], v[98:101]
	v_mfma_f32_16x16x32_bf16 v[86:89], v[178:181], v[222:225], v[86:89]
	v_mfma_f32_16x16x32_bf16 v[82:85], v[186:189], v[222:225], v[82:85]
	v_mfma_f32_16x16x32_bf16 v[70:73], v[178:181], v[230:233], v[70:73]
	v_mfma_f32_16x16x32_bf16 v[66:69], v[186:189], v[230:233], v[66:69]
	v_mfma_f32_16x16x32_bf16 v[118:121], v[182:185], v[210:213], v[118:121]
	v_mfma_f32_16x16x32_bf16 v[114:117], v[202:205], v[210:213], v[114:117]
	v_mfma_f32_16x16x32_bf16 v[102:105], v[182:185], v[218:221], v[102:105]
	v_mfma_f32_16x16x32_bf16 v[98:101], v[202:205], v[218:221], v[98:101]
	v_mfma_f32_16x16x32_bf16 v[86:89], v[182:185], v[226:229], v[86:89]
	v_mfma_f32_16x16x32_bf16 v[82:85], v[202:205], v[226:229], v[82:85]
	v_mfma_f32_16x16x32_bf16 v[70:73], v[182:185], v[234:237], v[70:73]
	v_mfma_f32_16x16x32_bf16 v[66:69], v[202:205], v[234:237], v[66:69]
	s_setprio 0
	s_barrier
; #define PG8_STAGE(bufoff, gbase, voff) do { _Pragma("unroll") for (int _i = 0; _i < 2; ++_i) \
;         __builtin_amdgcn_global_load_lds((const unsigned*)((const char*)(gbase) + (voff)[_i]), (PG8_LAS unsigned*)(lds + (bufoff) + ldsw + _i * 8192), 16, 0, 0); } while (0)
; #define PG8_LDA(dst, b, h) do { _Pragma("unroll") for (int m = 0; m < 4; ++m) _Pragma("unroll") for (int k = 0; k < 2; ++k) dst[m][k] = *(const PG8_LAS bf16x8*)(lds + PG8_SA(b, h) + aoff + m * 2048 + k * 1024); } while (0)
; #define PG8_MMA(ai, bj, At, Bt) do { __builtin_amdgcn_s_setprio(1); _Pragma("unroll") for (int m = 0; m < 4; ++m) _Pragma("unroll") for (int n = 0; n < 2; ++n) _Pragma("unroll") for (int k = 0; k < 2; ++k) \
;         acc[ai][bj][m][n] = __builtin_amdgcn_mfma_f32_16x16x32_bf16(Bt[n][k], At[m][k], acc[ai][bj][m][n], 0, 0, 0); __builtin_amdgcn_s_setprio(0); } while (0)
; #define PG8_WAIT_V(n) asm volatile("s_waitcnt vmcnt(" #n ")" ::: "memory")
; #define PG8_WAIT_L(n) asm volatile("s_waitcnt lgkmcnt(" #n ")" ::: "memory")
; #define PG8_BAR __builtin_amdgcn_s_barrier()
; #define PG8_SCHED __builtin_amdgcn_sched_barrier(0)
; template <class Epi, class Sched, bool ALIGN_EPI = false, bool SP2 = false>
; __device__ __forceinline__ void gemm_phase(PG8_LAS unsigned char* lds, const Gemm g, const Sched& S, const Epi& E, const int wid_in) {
;     ...
;             PG8_LDA(At, 1, 1); PG8_STAGE(PG8_SB(1, 0), b3, voffB); PG8_STAGE(PG8_SB(1, 1), b3 + hstep, voffB); PG8_STAGE(PG8_SA(1, 0), a3, voffA);
;             PG8_WAIT_V(8); PG8_WAIT_L(0); PG8_BAR; PG8_MMA(1, 0, At, B0); PG8_MMA(1, 1, At, B1); PG8_BAR; PG8_SCHED;
;     ...
;         if constexpr (ALIGN_EPI) { if (wr == 0) PG8_BAR; }
	s_add_i32 s2, s49, s29
	v_lshl_add_u64 v[150:151], v[150:151], 0, s[98:99]
	s_mov_b32 m0, s2
	ds_read_b128 v[206:209], v167 offset:49152
	ds_read_b128 v[210:213], v167 offset:50176
	ds_read_b128 v[214:217], v167 offset:51200
	ds_read_b128 v[218:221], v167 offset:52224
	ds_read_b128 v[222:225], v167 offset:53248
	ds_read_b128 v[226:229], v167 offset:54272
	ds_read_b128 v[230:233], v167 offset:55296
	ds_read_b128 v[234:237], v167 offset:56320
	global_load_lds_dwordx4 v[150:151], off
	s_add_i32 m0, s2, 0x2000
	s_add_u32 s0, s0, 0x80080
	v_lshl_add_u64 v[150:151], v[190:191], 0, s[98:99]
	s_addc_u32 s1, s1, 0
	s_add_i32 s2, s50, s29
	global_load_lds_dwordx4 v[150:151], off
	v_lshl_add_u64 v[150:151], s[0:1], 0, v[134:135]
	s_mov_b32 m0, s2
	s_nop 0
	global_load_lds_dwordx4 v[150:151], off
	v_lshl_add_u64 v[150:151], s[0:1], 0, v[130:131]
	s_add_i32 m0, s2, 0x2000
	s_nop 0
	global_load_lds_dwordx4 v[150:151], off
	v_lshl_add_u64 v[150:151], v[238:239], 0, s[98:99]
	s_mov_b32 m0, s39
	s_nop 0
	global_load_lds_dwordx4 v[150:151], off
	v_lshl_add_u64 v[150:151], v[240:241], 0, s[98:99]
	s_mov_b32 m0, s40
	s_nop 0
	global_load_lds_dwordx4 v[150:151], off
	s_waitcnt lgkmcnt(0)
	s_setprio 1
	s_waitcnt lgkmcnt(0)
	v_mfma_f32_16x16x32_bf16 v[62:65], v[142:145], v[206:209], v[62:65]
	v_mfma_f32_16x16x32_bf16 v[58:61], v[168:171], v[206:209], v[58:61]
	v_mfma_f32_16x16x32_bf16 v[46:49], v[142:145], v[214:217], v[46:49]
	v_mfma_f32_16x16x32_bf16 v[42:45], v[168:171], v[214:217], v[42:45]
	s_waitcnt vmcnt(8)
	s_barrier
	v_mfma_f32_16x16x32_bf16 v[30:33], v[142:145], v[222:225], v[30:33]
	v_mfma_f32_16x16x32_bf16 v[26:29], v[168:171], v[222:225], v[26:29]
	v_mfma_f32_16x16x32_bf16 v[14:17], v[142:145], v[230:233], v[14:17]
	v_mfma_f32_16x16x32_bf16 v[10:13], v[168:171], v[230:233], v[10:13]
	v_mfma_f32_16x16x32_bf16 v[62:65], v[146:149], v[210:213], v[62:65]
	v_mfma_f32_16x16x32_bf16 v[58:61], v[174:177], v[210:213], v[58:61]
	v_mfma_f32_16x16x32_bf16 v[46:49], v[146:149], v[218:221], v[46:49]
	v_mfma_f32_16x16x32_bf16 v[42:45], v[174:177], v[218:221], v[42:45]
	v_mfma_f32_16x16x32_bf16 v[30:33], v[146:149], v[226:229], v[30:33]
	v_mfma_f32_16x16x32_bf16 v[26:29], v[174:177], v[226:229], v[26:29]
	v_mfma_f32_16x16x32_bf16 v[14:17], v[146:149], v[234:237], v[14:17]
	v_mfma_f32_16x16x32_bf16 v[10:13], v[174:177], v[234:237], v[10:13]
	s_setprio 0
	s_setprio 1
	v_mfma_f32_16x16x32_bf16 v[54:57], v[178:181], v[206:209], v[54:57]
	v_mfma_f32_16x16x32_bf16 v[50:53], v[186:189], v[206:209], v[50:53]
	v_mfma_f32_16x16x32_bf16 v[38:41], v[178:181], v[214:217], v[38:41]
	v_mfma_f32_16x16x32_bf16 v[34:37], v[186:189], v[214:217], v[34:37]
	v_mfma_f32_16x16x32_bf16 v[22:25], v[178:181], v[222:225], v[22:25]
	v_mfma_f32_16x16x32_bf16 v[18:21], v[186:189], v[222:225], v[18:21]
	v_mfma_f32_16x16x32_bf16 v[6:9], v[178:181], v[230:233], v[6:9]
	v_mfma_f32_16x16x32_bf16 v[2:5], v[186:189], v[230:233], v[2:5]
	v_mfma_f32_16x16x32_bf16 v[54:57], v[182:185], v[210:213], v[54:57]
	v_mfma_f32_16x16x32_bf16 v[50:53], v[202:205], v[210:213], v[50:53]
	v_mfma_f32_16x16x32_bf16 v[38:41], v[182:185], v[218:221], v[38:41]
	v_mfma_f32_16x16x32_bf16 v[34:37], v[202:205], v[218:221], v[34:37]
	v_mfma_f32_16x16x32_bf16 v[22:25], v[182:185], v[226:229], v[22:25]
	v_mfma_f32_16x16x32_bf16 v[18:21], v[202:205], v[226:229], v[18:21]
	v_mfma_f32_16x16x32_bf16 v[6:9], v[182:185], v[234:237], v[6:9]
	v_mfma_f32_16x16x32_bf16 v[2:5], v[202:205], v[234:237], v[2:5]
	s_setprio 0
	s_barrier
	s_add_i32 s48, s48, 2
	s_add_u32 s24, s24, 0x100
	s_addc_u32 s25, s25, 0
	s_add_u32 s46, s46, 0x100
	s_addc_u32 s47, s47, 0
	s_cmp_gt_u32 s48, 29
	s_cbranch_scc0 .LBB0_484
	s_and_b64 vcc, exec, s[14:15]
	s_cbranch_vccz .LBB0_487
	s_barrier

; #define PG8_STAGE(bufoff, gbase, voff) do { _Pragma("unroll") for (int _i = 0; _i < 2; ++_i) \
;         __builtin_amdgcn_global_load_lds((const unsigned*)((const char*)(gbase) + (voff)[_i]), (PG8_LAS unsigned*)(lds + (bufoff) + ldsw + _i * 8192), 16, 0, 0); } while (0)
; #define PG8_LDA(dst, b, h) do { _Pragma("unroll") for (int m = 0; m < 4; ++m) _Pragma("unroll") for (int k = 0; k < 2; ++k) dst[m][k] = *(const PG8_LAS bf16x8*)(lds + PG8_SA(b, h) + aoff + m * 2048 + k * 1024); } while (0)
; #define PG8_LDB(dst, b, h) do { _Pragma("unroll") for (int n = 0; n < 2; ++n) _Pragma("unroll") for (int k = 0; k < 2; ++k) dst[n][k] = *(const PG8_LAS bf16x8*)(lds + PG8_SB(b, h) + boff + n * 2048 + k * 1024); } while (0)
; #define PG8_MMA(ai, bj, At, Bt) do { __builtin_amdgcn_s_setprio(1); _Pragma("unroll") for (int m = 0; m < 4; ++m) _Pragma("unroll") for (int n = 0; n < 2; ++n) _Pragma("unroll") for (int k = 0; k < 2; ++k) \
;         acc[ai][bj][m][n] = __builtin_amdgcn_mfma_f32_16x16x32_bf16(Bt[n][k], At[m][k], acc[ai][bj][m][n], 0, 0, 0); __builtin_amdgcn_s_setprio(0); } while (0)
; #define PG8_WAIT_V(n) asm volatile("s_waitcnt vmcnt(" #n ")" ::: "memory")
; #define PG8_WAIT_L(n) asm volatile("s_waitcnt lgkmcnt(" #n ")" ::: "memory")
; template <class Epi, class Sched, bool ALIGN_EPI = false, bool SP2 = false>
; __device__ __forceinline__ void gemm_phase(PG8_LAS unsigned char* lds, const Gemm g, const Sched& S, const Epi& E, const int wid_in) {
;     ...
;             const bool last = (t == nt - 2);
;             const char* a1 = cA + (size_t)(t + 1) * kstep;
;             const char* a2 = last ? nA : cA + (size_t)(t + 2) * kstep; const char* b2 = last ? nB : cB + (size_t)(t + 2) * kstep;
;             const char* a3 = a2 + kstep; const char* b3 = b2 + kstep;
;             if (last && has_next) S.a_ready(nxt);
;             if constexpr (SP2) {
;             PG8_LDB(B0, 0, 0); PG8_LDB(B1, 0, 1); PG8_SCHED; PG8_LDA(At, 0, 0); PG8_STAGE(PG8_SA(1, 1), a1 + hstepA, voffA);
;             PG8_WAIT_V(8); PG8_WAIT_L(0); PG8_BAR; PG8_MMA(0, 0, At, B0); PG8_MMA(0, 1, At, B1); PG8_BAR; PG8_SCHED;
;             PG8_LDA(At, 0, 1); PG8_STAGE(PG8_SB(0, 0), b2, voffB); PG8_STAGE(PG8_SB(0, 1), b2 + hstep, voffB); PG8_STAGE(PG8_SA(0, 0), a2, voffA);
;             PG8_WAIT_V(8); PG8_WAIT_L(0); PG8_BAR; PG8_MMA(1, 0, At, B0); PG8_MMA(1, 1, At, B1); PG8_BAR; PG8_SCHED;
.LBB0_545:
	s_add_u32 s2, s0, 0xffe00080
	s_addc_u32 s3, s1, -1
	s_add_i32 s49, 0, 0x10000
	s_cmpk_eq_i32 s48, 0x7c
	s_cselect_b32 s9, s21, s3
	s_cselect_b32 s8, s46, s2
	v_add_u32_e32 v145, s49, v147
	s_cselect_b32 s3, s19, s27
	s_cselect_b32 s2, s47, s26
	s_add_i32 s52, 0, 0x14000
	ds_read_b128 v[166:169], v145
	ds_read_b128 v[174:177], v145 offset:1024
	ds_read_b128 v[178:181], v145 offset:2048
	ds_read_b128 v[182:185], v145 offset:3072
	v_add_u32_e32 v145, s52, v147
	ds_read_b128 v[186:189], v145
	ds_read_b128 v[202:205], v145 offset:1024
	ds_read_b128 v[206:209], v145 offset:2048
	ds_read_b128 v[210:213], v145 offset:3072
	v_lshl_add_u64 v[152:153], s[0:1], 0, v[140:141]
	s_add_i32 m0, s36, 0xc000
	ds_read_b128 v[214:217], v150
	ds_read_b128 v[218:221], v150 offset:1024
	ds_read_b128 v[222:225], v150 offset:2048
	ds_read_b128 v[226:229], v150 offset:3072
	ds_read_b128 v[230:233], v150 offset:4096
	ds_read_b128 v[234:237], v150 offset:5120
	ds_read_b128 v[238:241], v150 offset:6144
	ds_read_b128 v[242:245], v150 offset:7168
	global_load_lds_dwordx4 v[152:153], off
	v_lshl_add_u64 v[152:153], s[0:1], 0, v[142:143]
	s_add_i32 m0, s36, 0xe000
	s_nop 0
	global_load_lds_dwordx4 v[152:153], off
	s_waitcnt lgkmcnt(0)
	s_setprio 1
	s_waitcnt lgkmcnt(0)
	v_mfma_f32_16x16x32_bf16 v[118:121], v[166:169], v[214:217], v[118:121]
	v_mfma_f32_16x16x32_bf16 v[114:117], v[178:181], v[214:217], v[114:117]
	v_mfma_f32_16x16x32_bf16 v[98:101], v[166:169], v[222:225], v[98:101]
	v_mfma_f32_16x16x32_bf16 v[106:109], v[178:181], v[222:225], v[106:109]
	s_waitcnt vmcnt(8)
	s_barrier
	v_mfma_f32_16x16x32_bf16 v[82:85], v[166:169], v[230:233], v[82:85]
	v_mfma_f32_16x16x32_bf16 v[90:93], v[178:181], v[230:233], v[90:93]
	v_mfma_f32_16x16x32_bf16 v[74:77], v[166:169], v[238:241], v[74:77]
	v_mfma_f32_16x16x32_bf16 v[66:69], v[178:181], v[238:241], v[66:69]
	v_mfma_f32_16x16x32_bf16 v[118:121], v[174:177], v[218:221], v[118:121]
	v_mfma_f32_16x16x32_bf16 v[114:117], v[182:185], v[218:221], v[114:117]
	v_mfma_f32_16x16x32_bf16 v[98:101], v[174:177], v[226:229], v[98:101]
	v_mfma_f32_16x16x32_bf16 v[106:109], v[182:185], v[226:229], v[106:109]
	v_mfma_f32_16x16x32_bf16 v[82:85], v[174:177], v[234:237], v[82:85]
	v_mfma_f32_16x16x32_bf16 v[90:93], v[182:185], v[234:237], v[90:93]
	v_mfma_f32_16x16x32_bf16 v[74:77], v[174:177], v[242:245], v[74:77]
	v_mfma_f32_16x16x32_bf16 v[66:69], v[182:185], v[242:245], v[66:69]
	s_setprio 0
	s_setprio 1
	v_mfma_f32_16x16x32_bf16 v[122:125], v[186:189], v[214:217], v[122:125]
	v_mfma_f32_16x16x32_bf16 v[126:129], v[206:209], v[214:217], v[126:129]
	v_mfma_f32_16x16x32_bf16 v[102:105], v[186:189], v[222:225], v[102:105]
	v_mfma_f32_16x16x32_bf16 v[110:113], v[206:209], v[222:225], v[110:113]
	v_mfma_f32_16x16x32_bf16 v[86:89], v[186:189], v[230:233], v[86:89]
	v_mfma_f32_16x16x32_bf16 v[94:97], v[206:209], v[230:233], v[94:97]
	v_mfma_f32_16x16x32_bf16 v[70:73], v[186:189], v[238:241], v[70:73]
	v_mfma_f32_16x16x32_bf16 v[78:81], v[206:209], v[238:241], v[78:81]
	v_mfma_f32_16x16x32_bf16 v[122:125], v[202:205], v[218:221], v[122:125]
	v_mfma_f32_16x16x32_bf16 v[126:129], v[210:213], v[218:221], v[126:129]
	v_mfma_f32_16x16x32_bf16 v[102:105], v[202:205], v[226:229], v[102:105]
	v_mfma_f32_16x16x32_bf16 v[110:113], v[210:213], v[226:229], v[110:113]
	v_mfma_f32_16x16x32_bf16 v[86:89], v[202:205], v[234:237], v[86:89]
	v_mfma_f32_16x16x32_bf16 v[94:97], v[210:213], v[234:237], v[94:97]
	v_mfma_f32_16x16x32_bf16 v[70:73], v[202:205], v[242:245], v[70:73]
	v_mfma_f32_16x16x32_bf16 v[78:81], v[210:213], v[242:245], v[78:81]
	s_setprio 0
	s_barrier
	s_add_i32 s49, s49, s35
	v_lshl_add_u64 v[152:153], s[2:3], 0, v[134:135]
	s_mov_b32 m0, s49
	ds_read_b128 v[214:217], v150 offset:16384
	ds_read_b128 v[218:221], v150 offset:17408
	ds_read_b128 v[222:225], v150 offset:18432
	ds_read_b128 v[226:229], v150 offset:19456
	ds_read_b128 v[230:233], v150 offset:20480
	ds_read_b128 v[234:237], v150 offset:21504
	ds_read_b128 v[238:241], v150 offset:22528
	ds_read_b128 v[242:245], v150 offset:23552
	global_load_lds_dwordx4 v[152:153], off
	s_add_i32 m0, s49, 0x2000
	s_add_u32 s50, s2, 0x200000
	v_lshl_add_u64 v[170:171], s[2:3], 0, v[130:131]
	s_addc_u32 s51, s3, 0
	s_add_i32 s49, s52, s35
	global_load_lds_dwordx4 v[170:171], off
	v_lshl_add_u64 v[190:191], s[50:51], 0, v[134:135]
	s_mov_b32 m0, s49
	v_lshl_add_u64 v[246:247], s[8:9], 0, v[132:133]
	global_load_lds_dwordx4 v[190:191], off
	v_lshl_add_u64 v[190:191], s[50:51], 0, v[130:131]
	s_add_i32 m0, s49, 0x2000
	s_nop 0
	global_load_lds_dwordx4 v[190:191], off
	v_lshl_add_u64 v[190:191], s[8:9], 0, v[136:137]
	s_mov_b32 m0, s36
	s_nop 0
	global_load_lds_dwordx4 v[190:191], off
	s_mov_b32 m0, s37
	s_nop 0
	global_load_lds_dwordx4 v[246:247], off
	s_waitcnt lgkmcnt(0)
	s_setprio 1
	s_waitcnt lgkmcnt(0)
	v_mfma_f32_16x16x32_bf16 v[34:37], v[166:169], v[214:217], v[34:37]
	v_mfma_f32_16x16x32_bf16 v[46:49], v[178:181], v[214:217], v[46:49]
	v_mfma_f32_16x16x32_bf16 v[10:13], v[166:169], v[222:225], v[10:13]
	v_mfma_f32_16x16x32_bf16 v[6:9], v[178:181], v[222:225], v[6:9]
	s_waitcnt vmcnt(8)
	s_barrier
; #define PG8_STAGE(bufoff, gbase, voff) do { _Pragma("unroll") for (int _i = 0; _i < 2; ++_i) \
;         __builtin_amdgcn_global_load_lds((const unsigned*)((const char*)(gbase) + (voff)[_i]), (PG8_LAS unsigned*)(lds + (bufoff) + ldsw + _i * 8192), 16, 0, 0); } while (0)
; #define PG8_LDA(dst, b, h) do { _Pragma("unroll") for (int m = 0; m < 4; ++m) _Pragma("unroll") for (int k = 0; k < 2; ++k) dst[m][k] = *(const PG8_LAS bf16x8*)(lds + PG8_SA(b, h) + aoff + m * 2048 + k * 1024); } while (0)
; #define PG8_LDB(dst, b, h) do { _Pragma("unroll") for (int n = 0; n < 2; ++n) _Pragma("unroll") for (int k = 0; k < 2; ++k) dst[n][k] = *(const PG8_LAS bf16x8*)(lds + PG8_SB(b, h) + boff + n * 2048 + k * 1024); } while (0)
; #define PG8_MMA(ai, bj, At, Bt) do { __builtin_amdgcn_s_setprio(1); _Pragma("unroll") for (int m = 0; m < 4; ++m) _Pragma("unroll") for (int n = 0; n < 2; ++n) _Pragma("unroll") for (int k = 0; k < 2; ++k) \
;         acc[ai][bj][m][n] = __builtin_amdgcn_mfma_f32_16x16x32_bf16(Bt[n][k], At[m][k], acc[ai][bj][m][n], 0, 0, 0); __builtin_amdgcn_s_setprio(0); } while (0)
; #define PG8_WAIT_V(n) asm volatile("s_waitcnt vmcnt(" #n ")" ::: "memory")
; #define PG8_WAIT_L(n) asm volatile("s_waitcnt lgkmcnt(" #n ")" ::: "memory")
; #define PG8_BAR __builtin_amdgcn_s_barrier()
; #define PG8_SCHED __builtin_amdgcn_sched_barrier(0)
; template <class Epi, class Sched, bool ALIGN_EPI = false, bool SP2 = false>
; __device__ __forceinline__ void gemm_phase(PG8_LAS unsigned char* lds, const Gemm g, const Sched& S, const Epi& E, const int wid_in) {
;     ...
;             PG8_WAIT_V(8); PG8_WAIT_L(0); PG8_BAR; PG8_MMA(1, 0, At, B0); PG8_MMA(1, 1, At, B1); PG8_BAR; PG8_SCHED;
;             PG8_LDB(B0, 1, 0); PG8_LDB(B1, 1, 1); PG8_SCHED; PG8_LDA(At, 1, 0); PG8_STAGE(PG8_SA(0, 1), a2 + hstepA, voffA);
;             PG8_WAIT_V(8); PG8_WAIT_L(0); PG8_BAR; PG8_MMA(0, 0, At, B0); PG8_MMA(0, 1, At, B1); PG8_BAR; PG8_SCHED;
	v_mfma_f32_16x16x32_bf16 v[42:45], v[166:169], v[230:233], v[42:45]
	v_mfma_f32_16x16x32_bf16 v[58:61], v[178:181], v[230:233], v[58:61]
	v_mfma_f32_16x16x32_bf16 v[22:25], v[166:169], v[238:241], v[22:25]
	v_mfma_f32_16x16x32_bf16 v[2:5], v[178:181], v[238:241], v[2:5]
	v_mfma_f32_16x16x32_bf16 v[34:37], v[174:177], v[218:221], v[34:37]
	v_mfma_f32_16x16x32_bf16 v[46:49], v[182:185], v[218:221], v[46:49]
	v_mfma_f32_16x16x32_bf16 v[10:13], v[174:177], v[226:229], v[10:13]
	v_mfma_f32_16x16x32_bf16 v[6:9], v[182:185], v[226:229], v[6:9]
	v_mfma_f32_16x16x32_bf16 v[42:45], v[174:177], v[234:237], v[42:45]
	v_mfma_f32_16x16x32_bf16 v[58:61], v[182:185], v[234:237], v[58:61]
	v_mfma_f32_16x16x32_bf16 v[22:25], v[174:177], v[242:245], v[22:25]
	v_mfma_f32_16x16x32_bf16 v[2:5], v[182:185], v[242:245], v[2:5]
	s_setprio 0
	s_setprio 1
	v_mfma_f32_16x16x32_bf16 v[38:41], v[186:189], v[214:217], v[38:41]
	v_mfma_f32_16x16x32_bf16 v[54:57], v[206:209], v[214:217], v[54:57]
	v_mfma_f32_16x16x32_bf16 v[14:17], v[186:189], v[222:225], v[14:17]
	v_mfma_f32_16x16x32_bf16 v[26:29], v[206:209], v[222:225], v[26:29]
	v_mfma_f32_16x16x32_bf16 v[50:53], v[186:189], v[230:233], v[50:53]
	v_mfma_f32_16x16x32_bf16 v[62:65], v[206:209], v[230:233], v[62:65]
	v_mfma_f32_16x16x32_bf16 v[18:21], v[186:189], v[238:241], v[18:21]
	v_mfma_f32_16x16x32_bf16 v[30:33], v[206:209], v[238:241], v[30:33]
	v_mfma_f32_16x16x32_bf16 v[38:41], v[202:205], v[218:221], v[38:41]
	v_mfma_f32_16x16x32_bf16 v[54:57], v[210:213], v[218:221], v[54:57]
	v_mfma_f32_16x16x32_bf16 v[14:17], v[202:205], v[226:229], v[14:17]
	v_mfma_f32_16x16x32_bf16 v[26:29], v[210:213], v[226:229], v[26:29]
	v_mfma_f32_16x16x32_bf16 v[50:53], v[202:205], v[234:237], v[50:53]
	v_mfma_f32_16x16x32_bf16 v[62:65], v[210:213], v[234:237], v[62:65]
	v_mfma_f32_16x16x32_bf16 v[18:21], v[202:205], v[242:245], v[18:21]
	v_mfma_f32_16x16x32_bf16 v[30:33], v[210:213], v[242:245], v[30:33]
	s_setprio 0
	s_barrier
	s_add_i32 s49, 0, 0x18000
	v_add_u32_e32 v145, s49, v147
	s_add_i32 s50, 0, 0x1c000
	ds_read_b128 v[166:169], v145
	ds_read_b128 v[174:177], v145 offset:1024
	ds_read_b128 v[178:181], v145 offset:2048
	ds_read_b128 v[182:185], v145 offset:3072
	v_add_u32_e32 v145, s50, v147
	ds_read_b128 v[186:189], v145
	ds_read_b128 v[202:205], v145 offset:1024
	ds_read_b128 v[206:209], v145 offset:2048
	ds_read_b128 v[210:213], v145 offset:3072
	s_add_u32 s8, s8, 0x200000
	s_addc_u32 s9, s9, 0
	s_mov_b32 m0, s38
	v_lshl_add_u64 v[248:249], s[8:9], 0, v[136:137]
	ds_read_b128 v[214:217], v150 offset:32768
	ds_read_b128 v[218:221], v150 offset:33792
	ds_read_b128 v[222:225], v150 offset:34816
	ds_read_b128 v[226:229], v150 offset:35840
	ds_read_b128 v[230:233], v150 offset:36864
	ds_read_b128 v[234:237], v150 offset:37888
	ds_read_b128 v[238:241], v150 offset:38912
	ds_read_b128 v[242:245], v150 offset:39936
	global_load_lds_dwordx4 v[248:249], off
	v_lshl_add_u64 v[248:249], s[8:9], 0, v[132:133]
	s_mov_b32 m0, s39
	s_nop 0
	global_load_lds_dwordx4 v[248:249], off
	s_waitcnt lgkmcnt(0)
	s_setprio 1
	s_waitcnt lgkmcnt(0)
	v_mfma_f32_16x16x32_bf16 v[118:121], v[166:169], v[214:217], v[118:121]
	v_mfma_f32_16x16x32_bf16 v[114:117], v[178:181], v[214:217], v[114:117]
	v_mfma_f32_16x16x32_bf16 v[98:101], v[166:169], v[222:225], v[98:101]
	v_mfma_f32_16x16x32_bf16 v[106:109], v[178:181], v[222:225], v[106:109]
	s_waitcnt vmcnt(8)
	s_barrier
	v_mfma_f32_16x16x32_bf16 v[82:85], v[166:169], v[230:233], v[82:85]
	v_mfma_f32_16x16x32_bf16 v[90:93], v[178:181], v[230:233], v[90:93]
	v_mfma_f32_16x16x32_bf16 v[74:77], v[166:169], v[238:241], v[74:77]
	v_mfma_f32_16x16x32_bf16 v[66:69], v[178:181], v[238:241], v[66:69]
	v_mfma_f32_16x16x32_bf16 v[118:121], v[174:177], v[218:221], v[118:121]
	v_mfma_f32_16x16x32_bf16 v[114:117], v[182:185], v[218:221], v[114:117]
	v_mfma_f32_16x16x32_bf16 v[98:101], v[174:177], v[226:229], v[98:101]
	v_mfma_f32_16x16x32_bf16 v[106:109], v[182:185], v[226:229], v[106:109]
	v_mfma_f32_16x16x32_bf16 v[82:85], v[174:177], v[234:237], v[82:85]
	v_mfma_f32_16x16x32_bf16 v[90:93], v[182:185], v[234:237], v[90:93]
	v_mfma_f32_16x16x32_bf16 v[74:77], v[174:177], v[242:245], v[74:77]
	v_mfma_f32_16x16x32_bf16 v[66:69], v[182:185], v[242:245], v[66:69]
	s_setprio 0
	s_setprio 1
	v_mfma_f32_16x16x32_bf16 v[122:125], v[186:189], v[214:217], v[122:125]
	v_mfma_f32_16x16x32_bf16 v[126:129], v[206:209], v[214:217], v[126:129]
	v_mfma_f32_16x16x32_bf16 v[102:105], v[186:189], v[222:225], v[102:105]
	v_mfma_f32_16x16x32_bf16 v[110:113], v[206:209], v[222:225], v[110:113]
	v_mfma_f32_16x16x32_bf16 v[86:89], v[186:189], v[230:233], v[86:89]
	v_mfma_f32_16x16x32_bf16 v[94:97], v[206:209], v[230:233], v[94:97]
	v_mfma_f32_16x16x32_bf16 v[70:73], v[186:189], v[238:241], v[70:73]
	v_mfma_f32_16x16x32_bf16 v[78:81], v[206:209], v[238:241], v[78:81]
	v_mfma_f32_16x16x32_bf16 v[122:125], v[202:205], v[218:221], v[122:125]
	v_mfma_f32_16x16x32_bf16 v[126:129], v[210:213], v[218:221], v[126:129]
	v_mfma_f32_16x16x32_bf16 v[102:105], v[202:205], v[226:229], v[102:105]
	v_mfma_f32_16x16x32_bf16 v[110:113], v[210:213], v[226:229], v[110:113]
	v_mfma_f32_16x16x32_bf16 v[86:89], v[202:205], v[234:237], v[86:89]
	v_mfma_f32_16x16x32_bf16 v[94:97], v[210:213], v[234:237], v[94:97]
	v_mfma_f32_16x16x32_bf16 v[70:73], v[202:205], v[242:245], v[70:73]
	v_mfma_f32_16x16x32_bf16 v[78:81], v[210:213], v[242:245], v[78:81]
	s_setprio 0
	s_barrier
; #define PG8_STAGE(bufoff, gbase, voff) do { _Pragma("unroll") for (int _i = 0; _i < 2; ++_i) \
;         __builtin_amdgcn_global_load_lds((const unsigned*)((const char*)(gbase) + (voff)[_i]), (PG8_LAS unsigned*)(lds + (bufoff) + ldsw + _i * 8192), 16, 0, 0); } while (0)
; #define PG8_LDA(dst, b, h) do { _Pragma("unroll") for (int m = 0; m < 4; ++m) _Pragma("unroll") for (int k = 0; k < 2; ++k) dst[m][k] = *(const PG8_LAS bf16x8*)(lds + PG8_SA(b, h) + aoff + m * 2048 + k * 1024); } while (0)
; #define PG8_MMA(ai, bj, At, Bt) do { __builtin_amdgcn_s_setprio(1); _Pragma("unroll") for (int m = 0; m < 4; ++m) _Pragma("unroll") for (int n = 0; n < 2; ++n) _Pragma("unroll") for (int k = 0; k < 2; ++k) \
;         acc[ai][bj][m][n] = __builtin_amdgcn_mfma_f32_16x16x32_bf16(Bt[n][k], At[m][k], acc[ai][bj][m][n], 0, 0, 0); __builtin_amdgcn_s_setprio(0); } while (0)
; #define PG8_WAIT_V(n) asm volatile("s_waitcnt vmcnt(" #n ")" ::: "memory")
; #define PG8_WAIT_L(n) asm volatile("s_waitcnt lgkmcnt(" #n ")" ::: "memory")
; #define PG8_BAR __builtin_amdgcn_s_barrier()
; #define PG8_SCHED __builtin_amdgcn_sched_barrier(0)
; template <class Epi, class Sched, bool ALIGN_EPI = false, bool SP2 = false>
; __device__ __forceinline__ void gemm_phase(PG8_LAS unsigned char* lds, const Gemm g, const Sched& S, const Epi& E, const int wid_in) {
;     ...
;             PG8_LDA(At, 1, 1); PG8_STAGE(PG8_SB(1, 0), b3, voffB); PG8_STAGE(PG8_SB(1, 1), b3 + hstep, voffB); PG8_STAGE(PG8_SA(1, 0), a3, voffA);
;             PG8_WAIT_V(8); PG8_WAIT_L(0); PG8_BAR; PG8_MMA(1, 0, At, B0); PG8_MMA(1, 1, At, B1); PG8_BAR; PG8_SCHED;
;     ...
;         if constexpr (ALIGN_EPI) { if (wr == 0) PG8_BAR; }
	s_add_i32 s8, s49, s35
	v_lshl_add_u64 v[152:153], v[152:153], 0, s[98:99]
	s_mov_b32 m0, s8
	ds_read_b128 v[214:217], v150 offset:49152
	ds_read_b128 v[218:221], v150 offset:50176
	ds_read_b128 v[222:225], v150 offset:51200
	ds_read_b128 v[226:229], v150 offset:52224
	ds_read_b128 v[230:233], v150 offset:53248
	ds_read_b128 v[234:237], v150 offset:54272
	ds_read_b128 v[238:241], v150 offset:55296
	ds_read_b128 v[242:245], v150 offset:56320
	global_load_lds_dwordx4 v[152:153], off
	s_add_i32 m0, s8, 0x2000
	s_add_u32 s2, s2, 0x200080
	v_lshl_add_u64 v[152:153], v[170:171], 0, s[98:99]
	s_addc_u32 s3, s3, 0
	s_add_i32 s8, s50, s35
	global_load_lds_dwordx4 v[152:153], off
	v_lshl_add_u64 v[152:153], s[2:3], 0, v[134:135]
	s_mov_b32 m0, s8
	s_nop 0
	global_load_lds_dwordx4 v[152:153], off
	v_lshl_add_u64 v[152:153], s[2:3], 0, v[130:131]
	s_add_i32 m0, s8, 0x2000
	s_nop 0
	global_load_lds_dwordx4 v[152:153], off
	v_lshl_add_u64 v[152:153], v[190:191], 0, s[98:99]
	s_mov_b32 m0, s42
	s_nop 0
	global_load_lds_dwordx4 v[152:153], off
	v_lshl_add_u64 v[152:153], v[246:247], 0, s[98:99]
	s_mov_b32 m0, s43
	s_nop 0
	global_load_lds_dwordx4 v[152:153], off
	s_waitcnt lgkmcnt(0)
	s_setprio 1
	s_waitcnt lgkmcnt(0)
	v_mfma_f32_16x16x32_bf16 v[34:37], v[166:169], v[214:217], v[34:37]
	v_mfma_f32_16x16x32_bf16 v[46:49], v[178:181], v[214:217], v[46:49]
	v_mfma_f32_16x16x32_bf16 v[10:13], v[166:169], v[222:225], v[10:13]
	v_mfma_f32_16x16x32_bf16 v[6:9], v[178:181], v[222:225], v[6:9]
	s_waitcnt vmcnt(8)
	s_barrier
	v_mfma_f32_16x16x32_bf16 v[42:45], v[166:169], v[230:233], v[42:45]
	v_mfma_f32_16x16x32_bf16 v[58:61], v[178:181], v[230:233], v[58:61]
	v_mfma_f32_16x16x32_bf16 v[22:25], v[166:169], v[238:241], v[22:25]
	v_mfma_f32_16x16x32_bf16 v[2:5], v[178:181], v[238:241], v[2:5]
	v_mfma_f32_16x16x32_bf16 v[34:37], v[174:177], v[218:221], v[34:37]
	v_mfma_f32_16x16x32_bf16 v[46:49], v[182:185], v[218:221], v[46:49]
	v_mfma_f32_16x16x32_bf16 v[10:13], v[174:177], v[226:229], v[10:13]
	v_mfma_f32_16x16x32_bf16 v[6:9], v[182:185], v[226:229], v[6:9]
	v_mfma_f32_16x16x32_bf16 v[42:45], v[174:177], v[234:237], v[42:45]
	v_mfma_f32_16x16x32_bf16 v[58:61], v[182:185], v[234:237], v[58:61]
	v_mfma_f32_16x16x32_bf16 v[22:25], v[174:177], v[242:245], v[22:25]
	v_mfma_f32_16x16x32_bf16 v[2:5], v[182:185], v[242:245], v[2:5]
	s_setprio 0
	s_setprio 1
	v_mfma_f32_16x16x32_bf16 v[38:41], v[186:189], v[214:217], v[38:41]
	v_mfma_f32_16x16x32_bf16 v[54:57], v[206:209], v[214:217], v[54:57]
	v_mfma_f32_16x16x32_bf16 v[14:17], v[186:189], v[222:225], v[14:17]
	v_mfma_f32_16x16x32_bf16 v[26:29], v[206:209], v[222:225], v[26:29]
	v_mfma_f32_16x16x32_bf16 v[50:53], v[186:189], v[230:233], v[50:53]
	v_mfma_f32_16x16x32_bf16 v[62:65], v[206:209], v[230:233], v[62:65]
	v_mfma_f32_16x16x32_bf16 v[18:21], v[186:189], v[238:241], v[18:21]
	v_mfma_f32_16x16x32_bf16 v[30:33], v[206:209], v[238:241], v[30:33]
	v_mfma_f32_16x16x32_bf16 v[38:41], v[202:205], v[218:221], v[38:41]
	v_mfma_f32_16x16x32_bf16 v[54:57], v[210:213], v[218:221], v[54:57]
	v_mfma_f32_16x16x32_bf16 v[14:17], v[202:205], v[226:229], v[14:17]
	v_mfma_f32_16x16x32_bf16 v[26:29], v[210:213], v[226:229], v[26:29]
	v_mfma_f32_16x16x32_bf16 v[50:53], v[202:205], v[234:237], v[50:53]
	v_mfma_f32_16x16x32_bf16 v[62:65], v[210:213], v[234:237], v[62:65]
	v_mfma_f32_16x16x32_bf16 v[18:21], v[202:205], v[242:245], v[18:21]
	v_mfma_f32_16x16x32_bf16 v[30:33], v[210:213], v[242:245], v[30:33]
	s_setprio 0
	s_barrier
	s_add_i32 s48, s48, 2
	s_add_u32 s0, s0, 0x100
	s_addc_u32 s1, s1, 0
	s_add_u32 s26, s26, 0x100
	s_addc_u32 s27, s27, 0
	s_cmpk_gt_u32 s48, 0x7d
	s_cbranch_scc0 .LBB0_545
	s_and_b64 vcc, exec, s[14:15]
	s_cbranch_vccz .LBB0_548
	s_barrier
